# GEMM K-loops: the two K-halves of each accumulator issued back to back (k0,k1 chained per accumulator) instead of all k0 then all k1
# speedup vs baseline: 1.0104x; 1.0025x over previous
.LBB0_260:
	v_add_u32_e32 v168, 0x10000, v232
	v_add_u32_e32 v180, 0x14000, v232
	v_lshl_add_u64 v[224:225], v[222:223], 0, s[62:63]
	s_add_i32 m0, s35, 0xc000
	s_waitcnt lgkmcnt(0)
	ds_read_b128 v[148:151], v207
	ds_read_b128 v[164:167], v207 offset:1024
	ds_read_b128 v[144:147], v207 offset:2048
	ds_read_b128 v[160:163], v207 offset:3072
	ds_read_b128 v[140:143], v207 offset:4096
	ds_read_b128 v[156:159], v207 offset:5120
	ds_read_b128 v[136:139], v207 offset:6144
	ds_read_b128 v[152:155], v207 offset:7168
	ds_read_b128 v[184:187], v168
	ds_read_b128 v[188:191], v168 offset:1024
	ds_read_b128 v[192:195], v168 offset:2048
	ds_read_b128 v[196:199], v168 offset:3072
	ds_read_b128 v[168:171], v180
	ds_read_b128 v[172:175], v180 offset:1024
	ds_read_b128 v[176:179], v180 offset:2048
	ds_read_b128 v[180:183], v180 offset:3072
	global_load_lds_dwordx4 v[224:225], off
	v_lshl_add_u64 v[224:225], v[220:221], 0, s[62:63]
	s_add_i32 m0, s35, 0xe000
	s_nop 0
	global_load_lds_dwordx4 v[224:225], off
	s_waitcnt vmcnt(8)
	s_waitcnt lgkmcnt(0)
	s_barrier
	s_setprio 1
	s_waitcnt lgkmcnt(0)
	v_mfma_f32_16x16x32_bf16 v[132:135], v[184:187], v[148:151], v[132:135]
	v_mfma_f32_16x16x32_bf16 v[132:135], v[188:191], v[164:167], v[132:135]
	v_mfma_f32_16x16x32_bf16 v[128:131], v[192:195], v[148:151], v[128:131]
	v_mfma_f32_16x16x32_bf16 v[128:131], v[196:199], v[164:167], v[128:131]
	v_mfma_f32_16x16x32_bf16 v[116:119], v[184:187], v[144:147], v[116:119]
	v_mfma_f32_16x16x32_bf16 v[116:119], v[188:191], v[160:163], v[116:119]
	v_mfma_f32_16x16x32_bf16 v[112:115], v[192:195], v[144:147], v[112:115]
	v_mfma_f32_16x16x32_bf16 v[112:115], v[196:199], v[160:163], v[112:115]
	v_mfma_f32_16x16x32_bf16 v[100:103], v[184:187], v[140:143], v[100:103]
	v_mfma_f32_16x16x32_bf16 v[100:103], v[188:191], v[156:159], v[100:103]
	v_mfma_f32_16x16x32_bf16 v[96:99], v[192:195], v[140:143], v[96:99]
	v_mfma_f32_16x16x32_bf16 v[96:99], v[196:199], v[156:159], v[96:99]
	v_mfma_f32_16x16x32_bf16 v[84:87], v[184:187], v[136:139], v[84:87]
	v_mfma_f32_16x16x32_bf16 v[84:87], v[188:191], v[152:155], v[84:87]
	v_mfma_f32_16x16x32_bf16 v[80:83], v[192:195], v[136:139], v[80:83]
	v_mfma_f32_16x16x32_bf16 v[80:83], v[196:199], v[152:155], v[80:83]
	s_setprio 0
	s_setprio 1
	v_mfma_f32_16x16x32_bf16 v[124:127], v[168:171], v[148:151], v[124:127]
	v_mfma_f32_16x16x32_bf16 v[124:127], v[172:175], v[164:167], v[124:127]
	v_mfma_f32_16x16x32_bf16 v[120:123], v[176:179], v[148:151], v[120:123]
	v_mfma_f32_16x16x32_bf16 v[120:123], v[180:183], v[164:167], v[120:123]
	v_mfma_f32_16x16x32_bf16 v[108:111], v[168:171], v[144:147], v[108:111]
	v_mfma_f32_16x16x32_bf16 v[108:111], v[172:175], v[160:163], v[108:111]
	v_mfma_f32_16x16x32_bf16 v[104:107], v[176:179], v[144:147], v[104:107]
	v_mfma_f32_16x16x32_bf16 v[104:107], v[180:183], v[160:163], v[104:107]
	v_mfma_f32_16x16x32_bf16 v[92:95], v[168:171], v[140:143], v[92:95]
	v_mfma_f32_16x16x32_bf16 v[92:95], v[172:175], v[156:159], v[92:95]
	v_mfma_f32_16x16x32_bf16 v[88:91], v[176:179], v[140:143], v[88:91]
	v_mfma_f32_16x16x32_bf16 v[88:91], v[180:183], v[156:159], v[88:91]
	v_mfma_f32_16x16x32_bf16 v[76:79], v[168:171], v[136:139], v[76:79]
	v_mfma_f32_16x16x32_bf16 v[76:79], v[172:175], v[152:155], v[76:79]
	v_mfma_f32_16x16x32_bf16 v[72:75], v[176:179], v[136:139], v[72:75]
	v_mfma_f32_16x16x32_bf16 v[72:75], v[180:183], v[152:155], v[72:75]
	s_setprio 0
	s_barrier
	v_cndmask_b32_e64 v204, 0, 1, s[60:61]
	v_cmp_ne_u32_e64 s[50:51], 1, v204
	s_andn2_b64 vcc, exec, s[60:61]
	s_cbranch_vccnz .LBB0_262
	ds_read_b128 v[148:151], v207 offset:16384
	ds_read_b128 v[164:167], v207 offset:17408
	ds_read_b128 v[144:147], v207 offset:18432
	ds_read_b128 v[160:163], v207 offset:19456
	ds_read_b128 v[140:143], v207 offset:20480
	ds_read_b128 v[156:159], v207 offset:21504
	ds_read_b128 v[136:139], v207 offset:22528
	ds_read_b128 v[152:155], v207 offset:23552
.LBB0_262:
	s_add_u32 s12, s58, s62
	s_addc_u32 s13, s59, s63
	s_add_u32 s14, s12, 0x100
	s_addc_u32 s15, s13, 0
	s_add_u32 s75, s26, s62
	s_addc_u32 s76, s27, s63
	s_cmpk_eq_i32 s62, 0xf00
	s_cselect_b64 s[52:53], -1, 0
	s_and_b64 s[12:13], s[52:53], exec
	s_cselect_b32 s13, s21, s76
	s_cselect_b32 s12, s73, s75
	s_mov_b32 m0, s38
	s_cselect_b32 s15, s25, s15
	s_cselect_b32 s14, s33, s14
	v_lshl_add_u64 v[224:225], s[12:13], 0, v[208:209]
	s_add_u32 s76, s12, 0x80000
	global_load_lds_dwordx4 v[224:225], off
	v_lshl_add_u64 v[226:227], s[12:13], 0, v[212:213]
	s_mov_b32 m0, s39
	s_addc_u32 s77, s13, 0
	global_load_lds_dwordx4 v[226:227], off
	v_lshl_add_u64 v[228:229], s[76:77], 0, v[208:209]
	s_mov_b32 m0, s40
	v_lshl_add_u64 v[230:231], s[14:15], 0, v[210:211]
	global_load_lds_dwordx4 v[228:229], off
	v_lshl_add_u64 v[228:229], s[76:77], 0, v[212:213]
	s_mov_b32 m0, s41
	s_and_b64 vcc, exec, s[50:51]
	global_load_lds_dwordx4 v[228:229], off
	v_lshl_add_u64 v[228:229], s[14:15], 0, v[4:5]
	s_mov_b32 m0, s35
	s_nop 0
	global_load_lds_dwordx4 v[228:229], off
	s_mov_b32 m0, s43
	s_nop 0
	global_load_lds_dwordx4 v[230:231], off
	s_waitcnt vmcnt(8)
	s_waitcnt lgkmcnt(0)
	s_barrier
	s_cbranch_vccnz .LBB0_264
	s_setprio 1
	s_waitcnt lgkmcnt(0)
	v_mfma_f32_16x16x32_bf16 v[68:71], v[184:187], v[148:151], v[68:71]
	v_mfma_f32_16x16x32_bf16 v[68:71], v[188:191], v[164:167], v[68:71]
	v_mfma_f32_16x16x32_bf16 v[64:67], v[192:195], v[148:151], v[64:67]
	v_mfma_f32_16x16x32_bf16 v[64:67], v[196:199], v[164:167], v[64:67]
	v_mfma_f32_16x16x32_bf16 v[52:55], v[184:187], v[144:147], v[52:55]
	v_mfma_f32_16x16x32_bf16 v[52:55], v[188:191], v[160:163], v[52:55]
	v_mfma_f32_16x16x32_bf16 v[48:51], v[192:195], v[144:147], v[48:51]
	v_mfma_f32_16x16x32_bf16 v[48:51], v[196:199], v[160:163], v[48:51]
	v_mfma_f32_16x16x32_bf16 v[36:39], v[184:187], v[140:143], v[36:39]
	v_mfma_f32_16x16x32_bf16 v[36:39], v[188:191], v[156:159], v[36:39]
	v_mfma_f32_16x16x32_bf16 v[32:35], v[192:195], v[140:143], v[32:35]
	v_mfma_f32_16x16x32_bf16 v[32:35], v[196:199], v[156:159], v[32:35]
	v_mfma_f32_16x16x32_bf16 v[20:23], v[184:187], v[136:139], v[20:23]
	v_mfma_f32_16x16x32_bf16 v[20:23], v[188:191], v[152:155], v[20:23]
	v_mfma_f32_16x16x32_bf16 v[16:19], v[192:195], v[136:139], v[16:19]
	v_mfma_f32_16x16x32_bf16 v[16:19], v[196:199], v[152:155], v[16:19]
	s_setprio 0
	s_setprio 1
	v_mfma_f32_16x16x32_bf16 v[60:63], v[168:171], v[148:151], v[60:63]
	v_mfma_f32_16x16x32_bf16 v[60:63], v[172:175], v[164:167], v[60:63]
	v_mfma_f32_16x16x32_bf16 v[56:59], v[176:179], v[148:151], v[56:59]
	v_mfma_f32_16x16x32_bf16 v[56:59], v[180:183], v[164:167], v[56:59]
	v_mfma_f32_16x16x32_bf16 v[44:47], v[168:171], v[144:147], v[44:47]
	v_mfma_f32_16x16x32_bf16 v[44:47], v[172:175], v[160:163], v[44:47]
	v_mfma_f32_16x16x32_bf16 v[40:43], v[176:179], v[144:147], v[40:43]
	v_mfma_f32_16x16x32_bf16 v[40:43], v[180:183], v[160:163], v[40:43]
	v_mfma_f32_16x16x32_bf16 v[28:31], v[168:171], v[140:143], v[28:31]
	v_mfma_f32_16x16x32_bf16 v[28:31], v[172:175], v[156:159], v[28:31]
	v_mfma_f32_16x16x32_bf16 v[24:27], v[176:179], v[140:143], v[24:27]
	v_mfma_f32_16x16x32_bf16 v[24:27], v[180:183], v[156:159], v[24:27]
	v_mfma_f32_16x16x32_bf16 v[12:15], v[168:171], v[136:139], v[12:15]
	v_mfma_f32_16x16x32_bf16 v[12:15], v[172:175], v[152:155], v[12:15]
	v_mfma_f32_16x16x32_bf16 v[8:11], v[176:179], v[136:139], v[8:11]
	v_mfma_f32_16x16x32_bf16 v[8:11], v[180:183], v[152:155], v[8:11]
	s_setprio 0
.LBB0_264:
	s_barrier
	v_cndmask_b32_e64 v241, v219, 0, s[52:53]
	v_cndmask_b32_e64 v240, v218, v2, s[52:53]
	v_lshl_add_u64 v[240:241], s[14:15], 0, v[240:241]
	s_mov_b32 m0, s45
	v_add_u32_e32 v168, 0x18000, v232
	v_add_u32_e32 v180, 0x1c000, v232
	v_lshl_add_u64 v[242:243], v[240:241], 0, v[4:5]
	s_waitcnt lgkmcnt(0)
	ds_read_b128 v[148:151], v207 offset:32768
	ds_read_b128 v[164:167], v207 offset:33792
	ds_read_b128 v[144:147], v207 offset:34816
	ds_read_b128 v[160:163], v207 offset:35840
	ds_read_b128 v[140:143], v207 offset:36864
	ds_read_b128 v[156:159], v207 offset:37888
	ds_read_b128 v[136:139], v207 offset:38912
	ds_read_b128 v[152:155], v207 offset:39936
	ds_read_b128 v[184:187], v168
	ds_read_b128 v[188:191], v168 offset:1024
	ds_read_b128 v[192:195], v168 offset:2048
	ds_read_b128 v[196:199], v168 offset:3072
	ds_read_b128 v[168:171], v180
	ds_read_b128 v[172:175], v180 offset:1024
	ds_read_b128 v[176:179], v180 offset:2048
	ds_read_b128 v[180:183], v180 offset:3072
	global_load_lds_dwordx4 v[242:243], off
	v_lshl_add_u64 v[240:241], v[240:241], 0, v[210:211]
	s_mov_b32 m0, s47
	s_nop 0
	global_load_lds_dwordx4 v[240:241], off
	s_waitcnt vmcnt(8)
	s_waitcnt lgkmcnt(0)
	s_barrier
	s_setprio 1
	s_waitcnt lgkmcnt(0)
	v_mfma_f32_16x16x32_bf16 v[132:135], v[184:187], v[148:151], v[132:135]
	v_mfma_f32_16x16x32_bf16 v[132:135], v[188:191], v[164:167], v[132:135]
	v_mfma_f32_16x16x32_bf16 v[128:131], v[192:195], v[148:151], v[128:131]
	v_mfma_f32_16x16x32_bf16 v[128:131], v[196:199], v[164:167], v[128:131]
	v_mfma_f32_16x16x32_bf16 v[116:119], v[184:187], v[144:147], v[116:119]
	v_mfma_f32_16x16x32_bf16 v[116:119], v[188:191], v[160:163], v[116:119]
	v_mfma_f32_16x16x32_bf16 v[112:115], v[192:195], v[144:147], v[112:115]
	v_mfma_f32_16x16x32_bf16 v[112:115], v[196:199], v[160:163], v[112:115]
	v_mfma_f32_16x16x32_bf16 v[100:103], v[184:187], v[140:143], v[100:103]
	v_mfma_f32_16x16x32_bf16 v[100:103], v[188:191], v[156:159], v[100:103]
	v_mfma_f32_16x16x32_bf16 v[96:99], v[192:195], v[140:143], v[96:99]
	v_mfma_f32_16x16x32_bf16 v[96:99], v[196:199], v[156:159], v[96:99]
	v_mfma_f32_16x16x32_bf16 v[84:87], v[184:187], v[136:139], v[84:87]
	v_mfma_f32_16x16x32_bf16 v[84:87], v[188:191], v[152:155], v[84:87]
	v_mfma_f32_16x16x32_bf16 v[80:83], v[192:195], v[136:139], v[80:83]
	v_mfma_f32_16x16x32_bf16 v[80:83], v[196:199], v[152:155], v[80:83]
	s_setprio 0
	s_setprio 1
	v_mfma_f32_16x16x32_bf16 v[124:127], v[168:171], v[148:151], v[124:127]
	v_mfma_f32_16x16x32_bf16 v[124:127], v[172:175], v[164:167], v[124:127]
	v_mfma_f32_16x16x32_bf16 v[120:123], v[176:179], v[148:151], v[120:123]
	v_mfma_f32_16x16x32_bf16 v[120:123], v[180:183], v[164:167], v[120:123]
	v_mfma_f32_16x16x32_bf16 v[108:111], v[168:171], v[144:147], v[108:111]
	v_mfma_f32_16x16x32_bf16 v[108:111], v[172:175], v[160:163], v[108:111]
	v_mfma_f32_16x16x32_bf16 v[104:107], v[176:179], v[144:147], v[104:107]
	v_mfma_f32_16x16x32_bf16 v[104:107], v[180:183], v[160:163], v[104:107]
	v_mfma_f32_16x16x32_bf16 v[92:95], v[168:171], v[140:143], v[92:95]
	v_mfma_f32_16x16x32_bf16 v[92:95], v[172:175], v[156:159], v[92:95]
	v_mfma_f32_16x16x32_bf16 v[88:91], v[176:179], v[140:143], v[88:91]
	v_mfma_f32_16x16x32_bf16 v[88:91], v[180:183], v[156:159], v[88:91]
	v_mfma_f32_16x16x32_bf16 v[76:79], v[168:171], v[136:139], v[76:79]
	v_mfma_f32_16x16x32_bf16 v[76:79], v[172:175], v[152:155], v[76:79]
	v_mfma_f32_16x16x32_bf16 v[72:75], v[176:179], v[136:139], v[72:75]
	v_mfma_f32_16x16x32_bf16 v[72:75], v[180:183], v[152:155], v[72:75]
	s_setprio 0
	s_barrier
	s_and_b64 vcc, exec, s[50:51]
	s_cbranch_vccnz .LBB0_266
	ds_read_b128 v[148:151], v207 offset:49152
	ds_read_b128 v[164:167], v207 offset:50176
	ds_read_b128 v[144:147], v207 offset:51200
	ds_read_b128 v[160:163], v207 offset:52224
	ds_read_b128 v[140:143], v207 offset:53248
	ds_read_b128 v[156:159], v207 offset:54272
	ds_read_b128 v[136:139], v207 offset:55296
	ds_read_b128 v[152:155], v207 offset:56320
.LBB0_266:
	s_mov_b32 m0, s64
	v_lshl_add_u64 v[224:225], v[224:225], 0, s[0:1]
	s_add_u32 s12, s12, 0x80080
	global_load_lds_dwordx4 v[224:225], off
	v_lshl_add_u64 v[224:225], v[226:227], 0, s[0:1]
	s_mov_b32 m0, s65
	s_addc_u32 s13, s13, 0
	global_load_lds_dwordx4 v[224:225], off
	v_lshl_add_u64 v[224:225], s[12:13], 0, v[208:209]
	s_mov_b32 m0, s68
	s_and_b64 vcc, exec, s[50:51]
	global_load_lds_dwordx4 v[224:225], off
	v_lshl_add_u64 v[224:225], s[12:13], 0, v[212:213]
	s_mov_b32 m0, s69
	s_nop 0
	global_load_lds_dwordx4 v[224:225], off
	v_lshl_add_u64 v[224:225], v[228:229], 0, s[0:1]
	s_mov_b32 m0, s66
	s_nop 0
	global_load_lds_dwordx4 v[224:225], off
	v_lshl_add_u64 v[224:225], v[230:231], 0, s[0:1]
	s_mov_b32 m0, s67
	s_nop 0
	global_load_lds_dwordx4 v[224:225], off
	s_waitcnt vmcnt(8)
	s_waitcnt lgkmcnt(0)
	s_barrier
	s_cbranch_vccnz .LBB0_259
	s_setprio 1
	s_waitcnt lgkmcnt(0)
	v_mfma_f32_16x16x32_bf16 v[68:71], v[184:187], v[148:151], v[68:71]
	v_mfma_f32_16x16x32_bf16 v[68:71], v[188:191], v[164:167], v[68:71]
	v_mfma_f32_16x16x32_bf16 v[64:67], v[192:195], v[148:151], v[64:67]
	v_mfma_f32_16x16x32_bf16 v[64:67], v[196:199], v[164:167], v[64:67]
	v_mfma_f32_16x16x32_bf16 v[52:55], v[184:187], v[144:147], v[52:55]
	v_mfma_f32_16x16x32_bf16 v[52:55], v[188:191], v[160:163], v[52:55]
	v_mfma_f32_16x16x32_bf16 v[48:51], v[192:195], v[144:147], v[48:51]
	v_mfma_f32_16x16x32_bf16 v[48:51], v[196:199], v[160:163], v[48:51]
	v_mfma_f32_16x16x32_bf16 v[36:39], v[184:187], v[140:143], v[36:39]
	v_mfma_f32_16x16x32_bf16 v[36:39], v[188:191], v[156:159], v[36:39]
	v_mfma_f32_16x16x32_bf16 v[32:35], v[192:195], v[140:143], v[32:35]
	v_mfma_f32_16x16x32_bf16 v[32:35], v[196:199], v[156:159], v[32:35]
	v_mfma_f32_16x16x32_bf16 v[20:23], v[184:187], v[136:139], v[20:23]
	v_mfma_f32_16x16x32_bf16 v[20:23], v[188:191], v[152:155], v[20:23]
	v_mfma_f32_16x16x32_bf16 v[16:19], v[192:195], v[136:139], v[16:19]
	v_mfma_f32_16x16x32_bf16 v[16:19], v[196:199], v[152:155], v[16:19]
	s_setprio 0
	s_setprio 1
	v_mfma_f32_16x16x32_bf16 v[60:63], v[168:171], v[148:151], v[60:63]
	v_mfma_f32_16x16x32_bf16 v[60:63], v[172:175], v[164:167], v[60:63]
	v_mfma_f32_16x16x32_bf16 v[56:59], v[176:179], v[148:151], v[56:59]
	v_mfma_f32_16x16x32_bf16 v[56:59], v[180:183], v[164:167], v[56:59]
	v_mfma_f32_16x16x32_bf16 v[44:47], v[168:171], v[144:147], v[44:47]
	v_mfma_f32_16x16x32_bf16 v[44:47], v[172:175], v[160:163], v[44:47]
	v_mfma_f32_16x16x32_bf16 v[40:43], v[176:179], v[144:147], v[40:43]
	v_mfma_f32_16x16x32_bf16 v[40:43], v[180:183], v[160:163], v[40:43]
	v_mfma_f32_16x16x32_bf16 v[28:31], v[168:171], v[140:143], v[28:31]
	v_mfma_f32_16x16x32_bf16 v[28:31], v[172:175], v[156:159], v[28:31]
	v_mfma_f32_16x16x32_bf16 v[24:27], v[176:179], v[140:143], v[24:27]
	v_mfma_f32_16x16x32_bf16 v[24:27], v[180:183], v[156:159], v[24:27]
	v_mfma_f32_16x16x32_bf16 v[12:15], v[168:171], v[136:139], v[12:15]
	v_mfma_f32_16x16x32_bf16 v[12:15], v[172:175], v[152:155], v[12:15]
	v_mfma_f32_16x16x32_bf16 v[8:11], v[176:179], v[136:139], v[8:11]
	v_mfma_f32_16x16x32_bf16 v[8:11], v[180:183], v[152:155], v[8:11]
	s_setprio 0
	s_branch .LBB0_259

.LBB0_369:
	v_add_u32_e32 v168, 0x10000, v232
	v_add_u32_e32 v180, 0x14000, v232
	v_lshl_add_u64 v[224:225], v[222:223], 0, s[60:61]
	s_add_i32 m0, s9, 0xc000
	s_waitcnt lgkmcnt(0)
	ds_read_b128 v[148:151], v207
	ds_read_b128 v[164:167], v207 offset:1024
	ds_read_b128 v[144:147], v207 offset:2048
	ds_read_b128 v[160:163], v207 offset:3072
	ds_read_b128 v[140:143], v207 offset:4096
	ds_read_b128 v[156:159], v207 offset:5120
	ds_read_b128 v[136:139], v207 offset:6144
	ds_read_b128 v[152:155], v207 offset:7168
	ds_read_b128 v[184:187], v168
	ds_read_b128 v[188:191], v168 offset:1024
	ds_read_b128 v[192:195], v168 offset:2048
	ds_read_b128 v[196:199], v168 offset:3072
	ds_read_b128 v[168:171], v180
	ds_read_b128 v[172:175], v180 offset:1024
	ds_read_b128 v[176:179], v180 offset:2048
	ds_read_b128 v[180:183], v180 offset:3072
	global_load_lds_dwordx4 v[224:225], off
	v_lshl_add_u64 v[224:225], v[220:221], 0, s[60:61]
	s_add_i32 m0, s9, 0xe000
	s_nop 0
	global_load_lds_dwordx4 v[224:225], off
	s_waitcnt vmcnt(8)
	s_waitcnt lgkmcnt(0)
	s_barrier
	s_setprio 1
	s_waitcnt lgkmcnt(0)
	v_mfma_f32_16x16x32_bf16 v[132:135], v[184:187], v[148:151], v[132:135]
	v_mfma_f32_16x16x32_bf16 v[132:135], v[188:191], v[164:167], v[132:135]
	v_mfma_f32_16x16x32_bf16 v[128:131], v[192:195], v[148:151], v[128:131]
	v_mfma_f32_16x16x32_bf16 v[128:131], v[196:199], v[164:167], v[128:131]
	v_mfma_f32_16x16x32_bf16 v[124:127], v[184:187], v[144:147], v[124:127]
	v_mfma_f32_16x16x32_bf16 v[124:127], v[188:191], v[160:163], v[124:127]
	v_mfma_f32_16x16x32_bf16 v[120:123], v[192:195], v[144:147], v[120:123]
	v_mfma_f32_16x16x32_bf16 v[120:123], v[196:199], v[160:163], v[120:123]
	v_mfma_f32_16x16x32_bf16 v[108:111], v[184:187], v[140:143], v[108:111]
	v_mfma_f32_16x16x32_bf16 v[108:111], v[188:191], v[156:159], v[108:111]
	v_mfma_f32_16x16x32_bf16 v[104:107], v[192:195], v[140:143], v[104:107]
	v_mfma_f32_16x16x32_bf16 v[104:107], v[196:199], v[156:159], v[104:107]
	v_mfma_f32_16x16x32_bf16 v[92:95], v[184:187], v[136:139], v[92:95]
	v_mfma_f32_16x16x32_bf16 v[92:95], v[188:191], v[152:155], v[92:95]
	v_mfma_f32_16x16x32_bf16 v[88:91], v[192:195], v[136:139], v[88:91]
	v_mfma_f32_16x16x32_bf16 v[88:91], v[196:199], v[152:155], v[88:91]
	s_setprio 0
	s_setprio 1
	v_mfma_f32_16x16x32_bf16 v[116:119], v[168:171], v[148:151], v[116:119]
	v_mfma_f32_16x16x32_bf16 v[116:119], v[172:175], v[164:167], v[116:119]
	v_mfma_f32_16x16x32_bf16 v[112:115], v[176:179], v[148:151], v[112:115]
	v_mfma_f32_16x16x32_bf16 v[112:115], v[180:183], v[164:167], v[112:115]
	v_mfma_f32_16x16x32_bf16 v[100:103], v[168:171], v[144:147], v[100:103]
	v_mfma_f32_16x16x32_bf16 v[100:103], v[172:175], v[160:163], v[100:103]
	v_mfma_f32_16x16x32_bf16 v[96:99], v[176:179], v[144:147], v[96:99]
	v_mfma_f32_16x16x32_bf16 v[96:99], v[180:183], v[160:163], v[96:99]
	v_mfma_f32_16x16x32_bf16 v[84:87], v[168:171], v[140:143], v[84:87]
	v_mfma_f32_16x16x32_bf16 v[84:87], v[172:175], v[156:159], v[84:87]
	v_mfma_f32_16x16x32_bf16 v[80:83], v[176:179], v[140:143], v[80:83]
	v_mfma_f32_16x16x32_bf16 v[80:83], v[180:183], v[156:159], v[80:83]
	v_mfma_f32_16x16x32_bf16 v[76:79], v[168:171], v[136:139], v[76:79]
	v_mfma_f32_16x16x32_bf16 v[76:79], v[172:175], v[152:155], v[76:79]
	v_mfma_f32_16x16x32_bf16 v[72:75], v[176:179], v[136:139], v[72:75]
	v_mfma_f32_16x16x32_bf16 v[72:75], v[180:183], v[152:155], v[72:75]
	s_setprio 0
	s_barrier
	v_cndmask_b32_e64 v204, 0, 1, s[58:59]
	v_cmp_ne_u32_e64 s[50:51], 1, v204
	s_andn2_b64 vcc, exec, s[58:59]
	s_cbranch_vccnz .LBB0_371
	ds_read_b128 v[148:151], v207 offset:16384
	ds_read_b128 v[164:167], v207 offset:17408
	ds_read_b128 v[144:147], v207 offset:18432
	ds_read_b128 v[160:163], v207 offset:19456
	ds_read_b128 v[140:143], v207 offset:20480
	ds_read_b128 v[156:159], v207 offset:21504
	ds_read_b128 v[136:139], v207 offset:22528
	ds_read_b128 v[152:155], v207 offset:23552
.LBB0_371:
	s_add_u32 s12, s24, s60
	s_addc_u32 s13, s25, s61
	s_add_u32 s14, s12, 0x100
	s_addc_u32 s15, s13, 0
	s_add_u32 s73, s26, s60
	s_addc_u32 s74, s27, s61
	s_cmpk_eq_i32 s60, 0xf00
	s_cselect_b64 s[52:53], -1, 0
	s_and_b64 s[12:13], s[52:53], exec
	s_cselect_b32 s13, s37, s74
	s_cselect_b32 s12, s43, s73
	s_mov_b32 m0, s38
	s_cselect_b32 s15, s7, s15
	s_cselect_b32 s14, s33, s14
	v_lshl_add_u64 v[224:225], s[12:13], 0, v[208:209]
	s_add_u32 s74, s12, 0x80000
	global_load_lds_dwordx4 v[224:225], off
	v_lshl_add_u64 v[226:227], s[12:13], 0, v[212:213]
	s_mov_b32 m0, s39
	s_addc_u32 s75, s13, 0
	global_load_lds_dwordx4 v[226:227], off
	v_lshl_add_u64 v[228:229], s[74:75], 0, v[208:209]
	s_mov_b32 m0, s40
	v_lshl_add_u64 v[230:231], s[14:15], 0, v[210:211]
	global_load_lds_dwordx4 v[228:229], off
	v_lshl_add_u64 v[228:229], s[74:75], 0, v[212:213]
	s_mov_b32 m0, s41
	s_and_b64 vcc, exec, s[50:51]
	global_load_lds_dwordx4 v[228:229], off
	v_lshl_add_u64 v[228:229], s[14:15], 0, v[4:5]
	s_mov_b32 m0, s9
	s_nop 0
	global_load_lds_dwordx4 v[228:229], off
	s_mov_b32 m0, s47
	s_nop 0
	global_load_lds_dwordx4 v[230:231], off
	s_waitcnt vmcnt(8)
	s_waitcnt lgkmcnt(0)
	s_barrier
	s_cbranch_vccnz .LBB0_373
	s_setprio 1
	s_waitcnt lgkmcnt(0)
	v_mfma_f32_16x16x32_bf16 v[68:71], v[184:187], v[148:151], v[68:71]
	v_mfma_f32_16x16x32_bf16 v[68:71], v[188:191], v[164:167], v[68:71]
	v_mfma_f32_16x16x32_bf16 v[64:67], v[192:195], v[148:151], v[64:67]
	v_mfma_f32_16x16x32_bf16 v[64:67], v[196:199], v[164:167], v[64:67]
	v_mfma_f32_16x16x32_bf16 v[52:55], v[184:187], v[144:147], v[52:55]
	v_mfma_f32_16x16x32_bf16 v[52:55], v[188:191], v[160:163], v[52:55]
	v_mfma_f32_16x16x32_bf16 v[48:51], v[192:195], v[144:147], v[48:51]
	v_mfma_f32_16x16x32_bf16 v[48:51], v[196:199], v[160:163], v[48:51]
	v_mfma_f32_16x16x32_bf16 v[36:39], v[184:187], v[140:143], v[36:39]
	v_mfma_f32_16x16x32_bf16 v[36:39], v[188:191], v[156:159], v[36:39]
	v_mfma_f32_16x16x32_bf16 v[32:35], v[192:195], v[140:143], v[32:35]
	v_mfma_f32_16x16x32_bf16 v[32:35], v[196:199], v[156:159], v[32:35]
	v_mfma_f32_16x16x32_bf16 v[20:23], v[184:187], v[136:139], v[20:23]
	v_mfma_f32_16x16x32_bf16 v[20:23], v[188:191], v[152:155], v[20:23]
	v_mfma_f32_16x16x32_bf16 v[16:19], v[192:195], v[136:139], v[16:19]
	v_mfma_f32_16x16x32_bf16 v[16:19], v[196:199], v[152:155], v[16:19]
	s_setprio 0
	s_setprio 1
	v_mfma_f32_16x16x32_bf16 v[60:63], v[168:171], v[148:151], v[60:63]
	v_mfma_f32_16x16x32_bf16 v[60:63], v[172:175], v[164:167], v[60:63]
	v_mfma_f32_16x16x32_bf16 v[56:59], v[176:179], v[148:151], v[56:59]
	v_mfma_f32_16x16x32_bf16 v[56:59], v[180:183], v[164:167], v[56:59]
	v_mfma_f32_16x16x32_bf16 v[44:47], v[168:171], v[144:147], v[44:47]
	v_mfma_f32_16x16x32_bf16 v[44:47], v[172:175], v[160:163], v[44:47]
	v_mfma_f32_16x16x32_bf16 v[40:43], v[176:179], v[144:147], v[40:43]
	v_mfma_f32_16x16x32_bf16 v[40:43], v[180:183], v[160:163], v[40:43]
	v_mfma_f32_16x16x32_bf16 v[28:31], v[168:171], v[140:143], v[28:31]
	v_mfma_f32_16x16x32_bf16 v[28:31], v[172:175], v[156:159], v[28:31]
	v_mfma_f32_16x16x32_bf16 v[24:27], v[176:179], v[140:143], v[24:27]
	v_mfma_f32_16x16x32_bf16 v[24:27], v[180:183], v[156:159], v[24:27]
	v_mfma_f32_16x16x32_bf16 v[12:15], v[168:171], v[136:139], v[12:15]
	v_mfma_f32_16x16x32_bf16 v[12:15], v[172:175], v[152:155], v[12:15]
	v_mfma_f32_16x16x32_bf16 v[8:11], v[176:179], v[136:139], v[8:11]
	v_mfma_f32_16x16x32_bf16 v[8:11], v[180:183], v[152:155], v[8:11]
	s_setprio 0
.LBB0_373:
	s_barrier
	v_cndmask_b32_e64 v241, v219, 0, s[52:53]
	v_cndmask_b32_e64 v240, v218, v2, s[52:53]
	v_lshl_add_u64 v[240:241], s[14:15], 0, v[240:241]
	s_mov_b32 m0, s62
	v_add_u32_e32 v168, 0x18000, v232
	v_add_u32_e32 v180, 0x1c000, v232
	v_lshl_add_u64 v[242:243], v[240:241], 0, v[4:5]
	s_waitcnt lgkmcnt(0)
	ds_read_b128 v[148:151], v207 offset:32768
	ds_read_b128 v[164:167], v207 offset:33792
	ds_read_b128 v[144:147], v207 offset:34816
	ds_read_b128 v[160:163], v207 offset:35840
	ds_read_b128 v[140:143], v207 offset:36864
	ds_read_b128 v[156:159], v207 offset:37888
	ds_read_b128 v[136:139], v207 offset:38912
	ds_read_b128 v[152:155], v207 offset:39936
	ds_read_b128 v[184:187], v168
	ds_read_b128 v[188:191], v168 offset:1024
	ds_read_b128 v[192:195], v168 offset:2048
	ds_read_b128 v[196:199], v168 offset:3072
	ds_read_b128 v[168:171], v180
	ds_read_b128 v[172:175], v180 offset:1024
	ds_read_b128 v[176:179], v180 offset:2048
	ds_read_b128 v[180:183], v180 offset:3072
	global_load_lds_dwordx4 v[242:243], off
	v_lshl_add_u64 v[240:241], v[240:241], 0, v[210:211]
	s_mov_b32 m0, s63
	s_nop 0
	global_load_lds_dwordx4 v[240:241], off
	s_waitcnt vmcnt(8)
	s_waitcnt lgkmcnt(0)
	s_barrier
	s_setprio 1
	s_waitcnt lgkmcnt(0)
	v_mfma_f32_16x16x32_bf16 v[132:135], v[184:187], v[148:151], v[132:135]
	v_mfma_f32_16x16x32_bf16 v[132:135], v[188:191], v[164:167], v[132:135]
	v_mfma_f32_16x16x32_bf16 v[128:131], v[192:195], v[148:151], v[128:131]
	v_mfma_f32_16x16x32_bf16 v[128:131], v[196:199], v[164:167], v[128:131]
	v_mfma_f32_16x16x32_bf16 v[124:127], v[184:187], v[144:147], v[124:127]
	v_mfma_f32_16x16x32_bf16 v[124:127], v[188:191], v[160:163], v[124:127]
	v_mfma_f32_16x16x32_bf16 v[120:123], v[192:195], v[144:147], v[120:123]
	v_mfma_f32_16x16x32_bf16 v[120:123], v[196:199], v[160:163], v[120:123]
	v_mfma_f32_16x16x32_bf16 v[108:111], v[184:187], v[140:143], v[108:111]
	v_mfma_f32_16x16x32_bf16 v[108:111], v[188:191], v[156:159], v[108:111]
	v_mfma_f32_16x16x32_bf16 v[104:107], v[192:195], v[140:143], v[104:107]
	v_mfma_f32_16x16x32_bf16 v[104:107], v[196:199], v[156:159], v[104:107]
	v_mfma_f32_16x16x32_bf16 v[92:95], v[184:187], v[136:139], v[92:95]
	v_mfma_f32_16x16x32_bf16 v[92:95], v[188:191], v[152:155], v[92:95]
	v_mfma_f32_16x16x32_bf16 v[88:91], v[192:195], v[136:139], v[88:91]
	v_mfma_f32_16x16x32_bf16 v[88:91], v[196:199], v[152:155], v[88:91]
	s_setprio 0
	s_setprio 1
	v_mfma_f32_16x16x32_bf16 v[116:119], v[168:171], v[148:151], v[116:119]
	v_mfma_f32_16x16x32_bf16 v[116:119], v[172:175], v[164:167], v[116:119]
	v_mfma_f32_16x16x32_bf16 v[112:115], v[176:179], v[148:151], v[112:115]
	v_mfma_f32_16x16x32_bf16 v[112:115], v[180:183], v[164:167], v[112:115]
	v_mfma_f32_16x16x32_bf16 v[100:103], v[168:171], v[144:147], v[100:103]
	v_mfma_f32_16x16x32_bf16 v[100:103], v[172:175], v[160:163], v[100:103]
	v_mfma_f32_16x16x32_bf16 v[96:99], v[176:179], v[144:147], v[96:99]
	v_mfma_f32_16x16x32_bf16 v[96:99], v[180:183], v[160:163], v[96:99]
	v_mfma_f32_16x16x32_bf16 v[84:87], v[168:171], v[140:143], v[84:87]
	v_mfma_f32_16x16x32_bf16 v[84:87], v[172:175], v[156:159], v[84:87]
	v_mfma_f32_16x16x32_bf16 v[80:83], v[176:179], v[140:143], v[80:83]
	v_mfma_f32_16x16x32_bf16 v[80:83], v[180:183], v[156:159], v[80:83]
	v_mfma_f32_16x16x32_bf16 v[76:79], v[168:171], v[136:139], v[76:79]
	v_mfma_f32_16x16x32_bf16 v[76:79], v[172:175], v[152:155], v[76:79]
	v_mfma_f32_16x16x32_bf16 v[72:75], v[176:179], v[136:139], v[72:75]
	v_mfma_f32_16x16x32_bf16 v[72:75], v[180:183], v[152:155], v[72:75]
	s_setprio 0
	s_barrier
	s_and_b64 vcc, exec, s[50:51]
	s_cbranch_vccnz .LBB0_375
	ds_read_b128 v[148:151], v207 offset:49152
	ds_read_b128 v[164:167], v207 offset:50176
	ds_read_b128 v[144:147], v207 offset:51200
	ds_read_b128 v[160:163], v207 offset:52224
	ds_read_b128 v[140:143], v207 offset:53248
	ds_read_b128 v[156:159], v207 offset:54272
	ds_read_b128 v[136:139], v207 offset:55296
	ds_read_b128 v[152:155], v207 offset:56320

.LBB0_559:
	v_add_u32_e32 v168, 0x10000, v240
	v_add_u32_e32 v180, 0x14000, v240
	v_lshl_add_u64 v[226:227], v[224:225], 0, s[64:65]
	s_add_i32 m0, s38, 0xc000
	s_waitcnt lgkmcnt(0)
	ds_read_b128 v[148:151], v239
	ds_read_b128 v[164:167], v239 offset:1024
	ds_read_b128 v[144:147], v239 offset:2048
	ds_read_b128 v[160:163], v239 offset:3072
	ds_read_b128 v[140:143], v239 offset:4096
	ds_read_b128 v[156:159], v239 offset:5120
	ds_read_b128 v[136:139], v239 offset:6144
	ds_read_b128 v[152:155], v239 offset:7168
	ds_read_b128 v[184:187], v168
	ds_read_b128 v[188:191], v168 offset:1024
	ds_read_b128 v[192:195], v168 offset:2048
	ds_read_b128 v[196:199], v168 offset:3072
	ds_read_b128 v[168:171], v180
	ds_read_b128 v[172:175], v180 offset:1024
	ds_read_b128 v[176:179], v180 offset:2048
	ds_read_b128 v[180:183], v180 offset:3072
	global_load_lds_dwordx4 v[226:227], off
	v_lshl_add_u64 v[226:227], v[222:223], 0, s[64:65]
	s_add_i32 m0, s38, 0xe000
	s_nop 0
	global_load_lds_dwordx4 v[226:227], off
	s_waitcnt vmcnt(8)
	s_waitcnt lgkmcnt(0)
	s_barrier
	s_setprio 1
	s_waitcnt lgkmcnt(0)
	v_mfma_f32_16x16x32_bf16 v[132:135], v[184:187], v[148:151], v[132:135]
	v_mfma_f32_16x16x32_bf16 v[132:135], v[188:191], v[164:167], v[132:135]
	v_mfma_f32_16x16x32_bf16 v[128:131], v[192:195], v[148:151], v[128:131]
	v_mfma_f32_16x16x32_bf16 v[128:131], v[196:199], v[164:167], v[128:131]
	v_mfma_f32_16x16x32_bf16 v[116:119], v[184:187], v[144:147], v[116:119]
	v_mfma_f32_16x16x32_bf16 v[116:119], v[188:191], v[160:163], v[116:119]
	v_mfma_f32_16x16x32_bf16 v[112:115], v[192:195], v[144:147], v[112:115]
	v_mfma_f32_16x16x32_bf16 v[112:115], v[196:199], v[160:163], v[112:115]
	v_mfma_f32_16x16x32_bf16 v[100:103], v[184:187], v[140:143], v[100:103]
	v_mfma_f32_16x16x32_bf16 v[100:103], v[188:191], v[156:159], v[100:103]
	v_mfma_f32_16x16x32_bf16 v[96:99], v[192:195], v[140:143], v[96:99]
	v_mfma_f32_16x16x32_bf16 v[96:99], v[196:199], v[156:159], v[96:99]
	v_mfma_f32_16x16x32_bf16 v[84:87], v[184:187], v[136:139], v[84:87]
	v_mfma_f32_16x16x32_bf16 v[84:87], v[188:191], v[152:155], v[84:87]
	v_mfma_f32_16x16x32_bf16 v[80:83], v[192:195], v[136:139], v[80:83]
	v_mfma_f32_16x16x32_bf16 v[80:83], v[196:199], v[152:155], v[80:83]
	s_setprio 0
	s_setprio 1
	v_mfma_f32_16x16x32_bf16 v[124:127], v[168:171], v[148:151], v[124:127]
	v_mfma_f32_16x16x32_bf16 v[124:127], v[172:175], v[164:167], v[124:127]
	v_mfma_f32_16x16x32_bf16 v[120:123], v[176:179], v[148:151], v[120:123]
	v_mfma_f32_16x16x32_bf16 v[120:123], v[180:183], v[164:167], v[120:123]
	v_mfma_f32_16x16x32_bf16 v[108:111], v[168:171], v[144:147], v[108:111]
	v_mfma_f32_16x16x32_bf16 v[108:111], v[172:175], v[160:163], v[108:111]
	v_mfma_f32_16x16x32_bf16 v[104:107], v[176:179], v[144:147], v[104:107]
	v_mfma_f32_16x16x32_bf16 v[104:107], v[180:183], v[160:163], v[104:107]
	v_mfma_f32_16x16x32_bf16 v[92:95], v[168:171], v[140:143], v[92:95]
	v_mfma_f32_16x16x32_bf16 v[92:95], v[172:175], v[156:159], v[92:95]
	v_mfma_f32_16x16x32_bf16 v[88:91], v[176:179], v[140:143], v[88:91]
	v_mfma_f32_16x16x32_bf16 v[88:91], v[180:183], v[156:159], v[88:91]
	v_mfma_f32_16x16x32_bf16 v[76:79], v[168:171], v[136:139], v[76:79]
	v_mfma_f32_16x16x32_bf16 v[76:79], v[172:175], v[152:155], v[76:79]
	v_mfma_f32_16x16x32_bf16 v[72:75], v[176:179], v[136:139], v[72:75]
	v_mfma_f32_16x16x32_bf16 v[72:75], v[180:183], v[152:155], v[72:75]
	s_setprio 0
	s_barrier
	v_cndmask_b32_e64 v204, 0, 1, s[62:63]
	v_cmp_ne_u32_e64 s[50:51], 1, v204
	s_andn2_b64 vcc, exec, s[62:63]
	s_cbranch_vccnz .LBB0_561
	ds_read_b128 v[148:151], v239 offset:16384
	ds_read_b128 v[164:167], v239 offset:17408
	ds_read_b128 v[144:147], v239 offset:18432
	ds_read_b128 v[160:163], v239 offset:19456
	ds_read_b128 v[140:143], v239 offset:20480
	ds_read_b128 v[156:159], v239 offset:21504
	ds_read_b128 v[136:139], v239 offset:22528
	ds_read_b128 v[152:155], v239 offset:23552
.LBB0_561:
	s_add_u32 s12, s60, s64
	s_addc_u32 s13, s61, s65
	s_add_u32 s14, s12, 0x100
	s_addc_u32 s15, s13, 0
	s_add_u32 s79, s26, s64
	s_addc_u32 s80, s27, s65
	s_cmpk_eq_i32 s64, 0x300
	s_cselect_b64 s[52:53], -1, 0
	s_and_b64 s[12:13], s[52:53], exec
	s_cselect_b32 s13, s17, s80
	s_cselect_b32 s12, s35, s79
	s_mov_b32 m0, s39
	s_cselect_b32 s15, s21, s15
	s_cselect_b32 s14, s33, s14
	v_lshl_add_u64 v[226:227], s[12:13], 0, v[4:5]
	s_add_u32 s80, s12, 0x20000
	global_load_lds_dwordx4 v[226:227], off
	v_lshl_add_u64 v[228:229], s[12:13], 0, v[208:209]
	s_mov_b32 m0, s40
	s_addc_u32 s81, s13, 0
	global_load_lds_dwordx4 v[228:229], off
	v_lshl_add_u64 v[230:231], s[80:81], 0, v[4:5]
	s_mov_b32 m0, s41
	v_lshl_add_u64 v[232:233], s[14:15], 0, v[208:209]
	global_load_lds_dwordx4 v[230:231], off
	v_lshl_add_u64 v[230:231], s[80:81], 0, v[208:209]
	s_mov_b32 m0, s47
	s_and_b64 vcc, exec, s[50:51]
	global_load_lds_dwordx4 v[230:231], off
	v_lshl_add_u64 v[230:231], s[14:15], 0, v[4:5]
	s_mov_b32 m0, s38
	s_nop 0
	global_load_lds_dwordx4 v[230:231], off
	s_mov_b32 m0, s59
	s_nop 0
	global_load_lds_dwordx4 v[232:233], off
	s_waitcnt vmcnt(8)
	s_waitcnt lgkmcnt(0)
	s_barrier
	s_cbranch_vccnz .LBB0_563
	s_setprio 1
	s_waitcnt lgkmcnt(0)
	v_mfma_f32_16x16x32_bf16 v[68:71], v[184:187], v[148:151], v[68:71]
	v_mfma_f32_16x16x32_bf16 v[68:71], v[188:191], v[164:167], v[68:71]
	v_mfma_f32_16x16x32_bf16 v[64:67], v[192:195], v[148:151], v[64:67]
	v_mfma_f32_16x16x32_bf16 v[64:67], v[196:199], v[164:167], v[64:67]
	v_mfma_f32_16x16x32_bf16 v[52:55], v[184:187], v[144:147], v[52:55]
	v_mfma_f32_16x16x32_bf16 v[52:55], v[188:191], v[160:163], v[52:55]
	v_mfma_f32_16x16x32_bf16 v[48:51], v[192:195], v[144:147], v[48:51]
	v_mfma_f32_16x16x32_bf16 v[48:51], v[196:199], v[160:163], v[48:51]
	v_mfma_f32_16x16x32_bf16 v[36:39], v[184:187], v[140:143], v[36:39]
	v_mfma_f32_16x16x32_bf16 v[36:39], v[188:191], v[156:159], v[36:39]
	v_mfma_f32_16x16x32_bf16 v[32:35], v[192:195], v[140:143], v[32:35]
	v_mfma_f32_16x16x32_bf16 v[32:35], v[196:199], v[156:159], v[32:35]
	v_mfma_f32_16x16x32_bf16 v[20:23], v[184:187], v[136:139], v[20:23]
	v_mfma_f32_16x16x32_bf16 v[20:23], v[188:191], v[152:155], v[20:23]
	v_mfma_f32_16x16x32_bf16 v[16:19], v[192:195], v[136:139], v[16:19]
	v_mfma_f32_16x16x32_bf16 v[16:19], v[196:199], v[152:155], v[16:19]
	s_setprio 0
	s_setprio 1
	v_mfma_f32_16x16x32_bf16 v[60:63], v[168:171], v[148:151], v[60:63]
	v_mfma_f32_16x16x32_bf16 v[60:63], v[172:175], v[164:167], v[60:63]
	v_mfma_f32_16x16x32_bf16 v[56:59], v[176:179], v[148:151], v[56:59]
	v_mfma_f32_16x16x32_bf16 v[56:59], v[180:183], v[164:167], v[56:59]
	v_mfma_f32_16x16x32_bf16 v[44:47], v[168:171], v[144:147], v[44:47]
	v_mfma_f32_16x16x32_bf16 v[44:47], v[172:175], v[160:163], v[44:47]
	v_mfma_f32_16x16x32_bf16 v[40:43], v[176:179], v[144:147], v[40:43]
	v_mfma_f32_16x16x32_bf16 v[40:43], v[180:183], v[160:163], v[40:43]
	v_mfma_f32_16x16x32_bf16 v[28:31], v[168:171], v[140:143], v[28:31]
	v_mfma_f32_16x16x32_bf16 v[28:31], v[172:175], v[156:159], v[28:31]
	v_mfma_f32_16x16x32_bf16 v[24:27], v[176:179], v[140:143], v[24:27]
	v_mfma_f32_16x16x32_bf16 v[24:27], v[180:183], v[156:159], v[24:27]
	v_mfma_f32_16x16x32_bf16 v[12:15], v[168:171], v[136:139], v[12:15]
	v_mfma_f32_16x16x32_bf16 v[12:15], v[172:175], v[152:155], v[12:15]
	v_mfma_f32_16x16x32_bf16 v[8:11], v[176:179], v[136:139], v[8:11]
	v_mfma_f32_16x16x32_bf16 v[8:11], v[180:183], v[152:155], v[8:11]
	s_setprio 0
.LBB0_563:
	s_barrier
	v_cndmask_b32_e64 v243, v221, 0, s[52:53]
	v_cndmask_b32_e64 v242, v220, v2, s[52:53]
	v_lshl_add_u64 v[242:243], s[14:15], 0, v[242:243]
	s_mov_b32 m0, s66
	v_add_u32_e32 v168, 0x18000, v240
	v_add_u32_e32 v180, 0x1c000, v240
	v_lshl_add_u64 v[204:205], v[242:243], 0, v[4:5]
	s_waitcnt lgkmcnt(0)
	ds_read_b128 v[148:151], v239 offset:32768
	ds_read_b128 v[164:167], v239 offset:33792
	ds_read_b128 v[144:147], v239 offset:34816
	ds_read_b128 v[160:163], v239 offset:35840
	ds_read_b128 v[140:143], v239 offset:36864
	ds_read_b128 v[156:159], v239 offset:37888
	ds_read_b128 v[136:139], v239 offset:38912
	ds_read_b128 v[152:155], v239 offset:39936
	ds_read_b128 v[184:187], v168
	ds_read_b128 v[188:191], v168 offset:1024
	ds_read_b128 v[192:195], v168 offset:2048
	ds_read_b128 v[196:199], v168 offset:3072
	ds_read_b128 v[168:171], v180
	ds_read_b128 v[172:175], v180 offset:1024
	ds_read_b128 v[176:179], v180 offset:2048
	ds_read_b128 v[180:183], v180 offset:3072
	global_load_lds_dwordx4 v[204:205], off
	v_lshl_add_u64 v[204:205], v[242:243], 0, v[208:209]
	s_mov_b32 m0, s67
	s_nop 0
	global_load_lds_dwordx4 v[204:205], off
	s_waitcnt vmcnt(8)
	s_waitcnt lgkmcnt(0)
	s_barrier
	s_setprio 1
	s_waitcnt lgkmcnt(0)
	v_mfma_f32_16x16x32_bf16 v[132:135], v[184:187], v[148:151], v[132:135]
	v_mfma_f32_16x16x32_bf16 v[132:135], v[188:191], v[164:167], v[132:135]
	v_mfma_f32_16x16x32_bf16 v[128:131], v[192:195], v[148:151], v[128:131]
	v_mfma_f32_16x16x32_bf16 v[128:131], v[196:199], v[164:167], v[128:131]
	v_mfma_f32_16x16x32_bf16 v[116:119], v[184:187], v[144:147], v[116:119]
	v_mfma_f32_16x16x32_bf16 v[116:119], v[188:191], v[160:163], v[116:119]
	v_mfma_f32_16x16x32_bf16 v[112:115], v[192:195], v[144:147], v[112:115]
	v_mfma_f32_16x16x32_bf16 v[112:115], v[196:199], v[160:163], v[112:115]
	v_mfma_f32_16x16x32_bf16 v[100:103], v[184:187], v[140:143], v[100:103]
	v_mfma_f32_16x16x32_bf16 v[100:103], v[188:191], v[156:159], v[100:103]
	v_mfma_f32_16x16x32_bf16 v[96:99], v[192:195], v[140:143], v[96:99]
	v_mfma_f32_16x16x32_bf16 v[96:99], v[196:199], v[156:159], v[96:99]
	v_mfma_f32_16x16x32_bf16 v[84:87], v[184:187], v[136:139], v[84:87]
	v_mfma_f32_16x16x32_bf16 v[84:87], v[188:191], v[152:155], v[84:87]
	v_mfma_f32_16x16x32_bf16 v[80:83], v[192:195], v[136:139], v[80:83]
	v_mfma_f32_16x16x32_bf16 v[80:83], v[196:199], v[152:155], v[80:83]
	s_setprio 0
	s_setprio 1
	v_mfma_f32_16x16x32_bf16 v[124:127], v[168:171], v[148:151], v[124:127]
	v_mfma_f32_16x16x32_bf16 v[124:127], v[172:175], v[164:167], v[124:127]
	v_mfma_f32_16x16x32_bf16 v[120:123], v[176:179], v[148:151], v[120:123]
	v_mfma_f32_16x16x32_bf16 v[120:123], v[180:183], v[164:167], v[120:123]
	v_mfma_f32_16x16x32_bf16 v[108:111], v[168:171], v[144:147], v[108:111]
	v_mfma_f32_16x16x32_bf16 v[108:111], v[172:175], v[160:163], v[108:111]
	v_mfma_f32_16x16x32_bf16 v[104:107], v[176:179], v[144:147], v[104:107]
	v_mfma_f32_16x16x32_bf16 v[104:107], v[180:183], v[160:163], v[104:107]
	v_mfma_f32_16x16x32_bf16 v[92:95], v[168:171], v[140:143], v[92:95]
	v_mfma_f32_16x16x32_bf16 v[92:95], v[172:175], v[156:159], v[92:95]
	v_mfma_f32_16x16x32_bf16 v[88:91], v[176:179], v[140:143], v[88:91]
	v_mfma_f32_16x16x32_bf16 v[88:91], v[180:183], v[156:159], v[88:91]
	v_mfma_f32_16x16x32_bf16 v[76:79], v[168:171], v[136:139], v[76:79]
	v_mfma_f32_16x16x32_bf16 v[76:79], v[172:175], v[152:155], v[76:79]
	v_mfma_f32_16x16x32_bf16 v[72:75], v[176:179], v[136:139], v[72:75]
	v_mfma_f32_16x16x32_bf16 v[72:75], v[180:183], v[152:155], v[72:75]
	s_setprio 0
	s_barrier
	s_and_b64 vcc, exec, s[50:51]
	s_cbranch_vccnz .LBB0_565
	ds_read_b128 v[148:151], v239 offset:49152
	ds_read_b128 v[164:167], v239 offset:50176
	ds_read_b128 v[144:147], v239 offset:51200
	ds_read_b128 v[160:163], v239 offset:52224
	ds_read_b128 v[140:143], v239 offset:53248
	ds_read_b128 v[156:159], v239 offset:54272
	ds_read_b128 v[136:139], v239 offset:55296
	ds_read_b128 v[152:155], v239 offset:56320
.LBB0_565:
	s_mov_b32 m0, s70
	v_lshl_add_u64 v[204:205], v[226:227], 0, s[0:1]
	s_add_u32 s12, s12, 0x20080
	global_load_lds_dwordx4 v[204:205], off
	v_lshl_add_u64 v[204:205], v[228:229], 0, s[0:1]
	s_mov_b32 m0, s71
	s_addc_u32 s13, s13, 0
	global_load_lds_dwordx4 v[204:205], off
	v_lshl_add_u64 v[204:205], s[12:13], 0, v[4:5]
	s_mov_b32 m0, s74
	s_and_b64 vcc, exec, s[50:51]
	global_load_lds_dwordx4 v[204:205], off
	v_lshl_add_u64 v[204:205], s[12:13], 0, v[208:209]
	s_mov_b32 m0, s75
	s_nop 0
	global_load_lds_dwordx4 v[204:205], off
	v_lshl_add_u64 v[204:205], v[230:231], 0, s[0:1]
	s_mov_b32 m0, s72
	s_nop 0
	global_load_lds_dwordx4 v[204:205], off
	v_lshl_add_u64 v[204:205], v[232:233], 0, s[0:1]
	s_mov_b32 m0, s73
	s_nop 0
	global_load_lds_dwordx4 v[204:205], off
	s_waitcnt vmcnt(8)
	s_waitcnt lgkmcnt(0)
	s_barrier
	s_cbranch_vccnz .LBB0_558
	s_setprio 1
	s_waitcnt lgkmcnt(0)
	v_mfma_f32_16x16x32_bf16 v[68:71], v[184:187], v[148:151], v[68:71]
	v_mfma_f32_16x16x32_bf16 v[68:71], v[188:191], v[164:167], v[68:71]
	v_mfma_f32_16x16x32_bf16 v[64:67], v[192:195], v[148:151], v[64:67]
	v_mfma_f32_16x16x32_bf16 v[64:67], v[196:199], v[164:167], v[64:67]
	v_mfma_f32_16x16x32_bf16 v[52:55], v[184:187], v[144:147], v[52:55]
	v_mfma_f32_16x16x32_bf16 v[52:55], v[188:191], v[160:163], v[52:55]
	v_mfma_f32_16x16x32_bf16 v[48:51], v[192:195], v[144:147], v[48:51]
	v_mfma_f32_16x16x32_bf16 v[48:51], v[196:199], v[160:163], v[48:51]
	v_mfma_f32_16x16x32_bf16 v[36:39], v[184:187], v[140:143], v[36:39]
	v_mfma_f32_16x16x32_bf16 v[36:39], v[188:191], v[156:159], v[36:39]
	v_mfma_f32_16x16x32_bf16 v[32:35], v[192:195], v[140:143], v[32:35]
	v_mfma_f32_16x16x32_bf16 v[32:35], v[196:199], v[156:159], v[32:35]
	v_mfma_f32_16x16x32_bf16 v[20:23], v[184:187], v[136:139], v[20:23]
	v_mfma_f32_16x16x32_bf16 v[20:23], v[188:191], v[152:155], v[20:23]
	v_mfma_f32_16x16x32_bf16 v[16:19], v[192:195], v[136:139], v[16:19]
	v_mfma_f32_16x16x32_bf16 v[16:19], v[196:199], v[152:155], v[16:19]
	s_setprio 0
	s_setprio 1
	v_mfma_f32_16x16x32_bf16 v[60:63], v[168:171], v[148:151], v[60:63]
	v_mfma_f32_16x16x32_bf16 v[60:63], v[172:175], v[164:167], v[60:63]
	v_mfma_f32_16x16x32_bf16 v[56:59], v[176:179], v[148:151], v[56:59]
	v_mfma_f32_16x16x32_bf16 v[56:59], v[180:183], v[164:167], v[56:59]
	v_mfma_f32_16x16x32_bf16 v[44:47], v[168:171], v[144:147], v[44:47]
	v_mfma_f32_16x16x32_bf16 v[44:47], v[172:175], v[160:163], v[44:47]
	v_mfma_f32_16x16x32_bf16 v[40:43], v[176:179], v[144:147], v[40:43]
	v_mfma_f32_16x16x32_bf16 v[40:43], v[180:183], v[160:163], v[40:43]
	v_mfma_f32_16x16x32_bf16 v[28:31], v[168:171], v[140:143], v[28:31]
	v_mfma_f32_16x16x32_bf16 v[28:31], v[172:175], v[156:159], v[28:31]
	v_mfma_f32_16x16x32_bf16 v[24:27], v[176:179], v[140:143], v[24:27]
	v_mfma_f32_16x16x32_bf16 v[24:27], v[180:183], v[156:159], v[24:27]
	v_mfma_f32_16x16x32_bf16 v[12:15], v[168:171], v[136:139], v[12:15]
	v_mfma_f32_16x16x32_bf16 v[12:15], v[172:175], v[152:155], v[12:15]
	v_mfma_f32_16x16x32_bf16 v[8:11], v[176:179], v[136:139], v[8:11]
	v_mfma_f32_16x16x32_bf16 v[8:11], v[180:183], v[152:155], v[8:11]
	s_setprio 0
	s_branch .LBB0_558

.LBB0_620:
	s_add_u32 s12, s42, 0xfffe0080
	s_addc_u32 s13, s43, -1
	s_cmp_eq_u32 s57, 4
	s_cselect_b32 s15, s17, s13
	s_cselect_b32 s14, s33, s12
	s_cselect_b32 s13, s11, s27
	s_cselect_b32 s12, s37, s26
	s_add_i32 s58, 0, 0x10000
	v_add_u32_e32 v136, s58, v1
	s_add_i32 s60, 0, 0x14000
	ds_read_b128 v[150:153], v7
	ds_read_b128 v[154:157], v7 offset:1024
	ds_read_b128 v[158:161], v7 offset:2048
	ds_read_b128 v[162:165], v7 offset:3072
	ds_read_b128 v[166:169], v7 offset:4096
	ds_read_b128 v[170:173], v7 offset:5120
	ds_read_b128 v[174:177], v7 offset:6144
	ds_read_b128 v[178:181], v7 offset:7168
	ds_read_b128 v[182:185], v136
	ds_read_b128 v[186:189], v136 offset:1024
	ds_read_b128 v[190:193], v136 offset:2048
	ds_read_b128 v[194:197], v136 offset:3072
	v_add_u32_e32 v136, s60, v1
	ds_read_b128 v[208:211], v136
	ds_read_b128 v[212:215], v136 offset:1024
	ds_read_b128 v[216:219], v136 offset:2048
	ds_read_b128 v[220:223], v136 offset:3072
	v_lshl_add_u64 v[136:137], s[42:43], 0, v[146:147]
	s_add_i32 m0, s38, 0xc000
	s_nop 0
	global_load_lds_dwordx4 v[136:137], off
	v_lshl_add_u64 v[136:137], s[42:43], 0, v[148:149]
	s_add_i32 m0, s38, 0xe000
	s_nop 0
	global_load_lds_dwordx4 v[136:137], off
	s_waitcnt vmcnt(8)
	s_waitcnt lgkmcnt(0)
	s_barrier
	s_setprio 1
	s_waitcnt lgkmcnt(0)
	v_mfma_f32_16x16x32_bf16 v[132:135], v[182:185], v[150:153], v[132:135]
	v_mfma_f32_16x16x32_bf16 v[132:135], v[186:189], v[154:157], v[132:135]
	v_mfma_f32_16x16x32_bf16 v[128:131], v[190:193], v[150:153], v[128:131]
	v_mfma_f32_16x16x32_bf16 v[128:131], v[194:197], v[154:157], v[128:131]
	v_mfma_f32_16x16x32_bf16 v[124:127], v[182:185], v[158:161], v[124:127]
	v_mfma_f32_16x16x32_bf16 v[124:127], v[186:189], v[162:165], v[124:127]
	v_mfma_f32_16x16x32_bf16 v[120:123], v[190:193], v[158:161], v[120:123]
	v_mfma_f32_16x16x32_bf16 v[120:123], v[194:197], v[162:165], v[120:123]
	v_mfma_f32_16x16x32_bf16 v[116:119], v[182:185], v[166:169], v[116:119]
	v_mfma_f32_16x16x32_bf16 v[116:119], v[186:189], v[170:173], v[116:119]
	v_mfma_f32_16x16x32_bf16 v[108:111], v[190:193], v[166:169], v[108:111]
	v_mfma_f32_16x16x32_bf16 v[108:111], v[194:197], v[170:173], v[108:111]
	v_mfma_f32_16x16x32_bf16 v[100:103], v[182:185], v[174:177], v[100:103]
	v_mfma_f32_16x16x32_bf16 v[100:103], v[186:189], v[178:181], v[100:103]
	v_mfma_f32_16x16x32_bf16 v[92:95], v[190:193], v[174:177], v[92:95]
	v_mfma_f32_16x16x32_bf16 v[92:95], v[194:197], v[178:181], v[92:95]
	s_setprio 0
	s_setprio 1
	v_mfma_f32_16x16x32_bf16 v[112:115], v[208:211], v[150:153], v[112:115]
	v_mfma_f32_16x16x32_bf16 v[112:115], v[212:215], v[154:157], v[112:115]
	v_mfma_f32_16x16x32_bf16 v[104:107], v[216:219], v[150:153], v[104:107]
	v_mfma_f32_16x16x32_bf16 v[104:107], v[220:223], v[154:157], v[104:107]
	v_mfma_f32_16x16x32_bf16 v[96:99], v[208:211], v[158:161], v[96:99]
	v_mfma_f32_16x16x32_bf16 v[96:99], v[212:215], v[162:165], v[96:99]
	v_mfma_f32_16x16x32_bf16 v[88:91], v[216:219], v[158:161], v[88:91]
	v_mfma_f32_16x16x32_bf16 v[88:91], v[220:223], v[162:165], v[88:91]
	v_mfma_f32_16x16x32_bf16 v[84:87], v[208:211], v[166:169], v[84:87]
	v_mfma_f32_16x16x32_bf16 v[84:87], v[212:215], v[170:173], v[84:87]
	v_mfma_f32_16x16x32_bf16 v[80:83], v[216:219], v[166:169], v[80:83]
	v_mfma_f32_16x16x32_bf16 v[80:83], v[220:223], v[170:173], v[80:83]
	v_mfma_f32_16x16x32_bf16 v[76:79], v[208:211], v[174:177], v[76:79]
	v_mfma_f32_16x16x32_bf16 v[76:79], v[212:215], v[178:181], v[76:79]
	v_mfma_f32_16x16x32_bf16 v[72:75], v[216:219], v[174:177], v[72:75]
	v_mfma_f32_16x16x32_bf16 v[72:75], v[220:223], v[178:181], v[72:75]
	s_setprio 0
	s_barrier
	s_add_i32 s58, s58, s35
	v_lshl_add_u64 v[136:137], s[12:13], 0, v[2:3]
	s_mov_b32 m0, s58
	ds_read_b128 v[150:153], v7 offset:16384
	ds_read_b128 v[154:157], v7 offset:17408
	ds_read_b128 v[158:161], v7 offset:18432
	ds_read_b128 v[162:165], v7 offset:19456
	ds_read_b128 v[166:169], v7 offset:20480
	ds_read_b128 v[170:173], v7 offset:21504
	ds_read_b128 v[174:177], v7 offset:22528
	ds_read_b128 v[178:181], v7 offset:23552
	global_load_lds_dwordx4 v[136:137], off
	s_add_i32 m0, s58, 0x2000
	s_add_u32 s58, s12, 0x20000
	v_lshl_add_u64 v[198:199], s[12:13], 0, v[4:5]
	s_addc_u32 s59, s13, 0
	s_add_i32 s60, s60, s35
	global_load_lds_dwordx4 v[198:199], off
	v_lshl_add_u64 v[204:205], s[58:59], 0, v[2:3]
	s_mov_b32 m0, s60
	v_lshl_add_u64 v[224:225], s[14:15], 0, v[138:139]
	global_load_lds_dwordx4 v[204:205], off
	v_lshl_add_u64 v[204:205], s[58:59], 0, v[4:5]
	s_add_i32 m0, s60, 0x2000
	s_nop 0
	global_load_lds_dwordx4 v[204:205], off
	v_lshl_add_u64 v[204:205], s[14:15], 0, v[140:141]
	s_mov_b32 m0, s38
	s_nop 0
	global_load_lds_dwordx4 v[204:205], off
	s_mov_b32 m0, s39
	s_nop 0
	global_load_lds_dwordx4 v[224:225], off
	s_waitcnt vmcnt(8)
	s_waitcnt lgkmcnt(0)
	s_barrier
	s_setprio 1
	s_waitcnt lgkmcnt(0)
	v_mfma_f32_16x16x32_bf16 v[68:71], v[182:185], v[150:153], v[68:71]
	v_mfma_f32_16x16x32_bf16 v[68:71], v[186:189], v[154:157], v[68:71]
	v_mfma_f32_16x16x32_bf16 v[64:67], v[190:193], v[150:153], v[64:67]
	v_mfma_f32_16x16x32_bf16 v[64:67], v[194:197], v[154:157], v[64:67]
	v_mfma_f32_16x16x32_bf16 v[60:63], v[182:185], v[158:161], v[60:63]
	v_mfma_f32_16x16x32_bf16 v[60:63], v[186:189], v[162:165], v[60:63]
	v_mfma_f32_16x16x32_bf16 v[56:59], v[190:193], v[158:161], v[56:59]
	v_mfma_f32_16x16x32_bf16 v[56:59], v[194:197], v[162:165], v[56:59]
	v_mfma_f32_16x16x32_bf16 v[52:55], v[182:185], v[166:169], v[52:55]
	v_mfma_f32_16x16x32_bf16 v[52:55], v[186:189], v[170:173], v[52:55]
	v_mfma_f32_16x16x32_bf16 v[44:47], v[190:193], v[166:169], v[44:47]
	v_mfma_f32_16x16x32_bf16 v[44:47], v[194:197], v[170:173], v[44:47]
	v_mfma_f32_16x16x32_bf16 v[36:39], v[182:185], v[174:177], v[36:39]
	v_mfma_f32_16x16x32_bf16 v[36:39], v[186:189], v[178:181], v[36:39]
	v_mfma_f32_16x16x32_bf16 v[28:31], v[190:193], v[174:177], v[28:31]
	v_mfma_f32_16x16x32_bf16 v[28:31], v[194:197], v[178:181], v[28:31]
	s_setprio 0
	s_setprio 1
	v_mfma_f32_16x16x32_bf16 v[48:51], v[208:211], v[150:153], v[48:51]
	v_mfma_f32_16x16x32_bf16 v[48:51], v[212:215], v[154:157], v[48:51]
	v_mfma_f32_16x16x32_bf16 v[40:43], v[216:219], v[150:153], v[40:43]
	v_mfma_f32_16x16x32_bf16 v[40:43], v[220:223], v[154:157], v[40:43]
	v_mfma_f32_16x16x32_bf16 v[32:35], v[208:211], v[158:161], v[32:35]
	v_mfma_f32_16x16x32_bf16 v[32:35], v[212:215], v[162:165], v[32:35]
	v_mfma_f32_16x16x32_bf16 v[24:27], v[216:219], v[158:161], v[24:27]
	v_mfma_f32_16x16x32_bf16 v[24:27], v[220:223], v[162:165], v[24:27]
	v_mfma_f32_16x16x32_bf16 v[20:23], v[208:211], v[166:169], v[20:23]
	v_mfma_f32_16x16x32_bf16 v[20:23], v[212:215], v[170:173], v[20:23]
	v_mfma_f32_16x16x32_bf16 v[16:19], v[216:219], v[166:169], v[16:19]
	v_mfma_f32_16x16x32_bf16 v[16:19], v[220:223], v[170:173], v[16:19]
	v_mfma_f32_16x16x32_bf16 v[12:15], v[208:211], v[174:177], v[12:15]
	v_mfma_f32_16x16x32_bf16 v[12:15], v[212:215], v[178:181], v[12:15]
	v_mfma_f32_16x16x32_bf16 v[8:11], v[216:219], v[174:177], v[8:11]
	v_mfma_f32_16x16x32_bf16 v[8:11], v[220:223], v[178:181], v[8:11]
	s_setprio 0
	s_barrier
	s_add_i32 s58, 0, 0x18000
	s_add_i32 s59, 0, 0x1c000
	s_add_u32 s14, s14, 0x20000
	s_addc_u32 s15, s15, 0
	s_mov_b32 m0, s40
	v_add_u32_e32 v194, s58, v1
	v_add_u32_e32 v207, s59, v1
	v_lshl_add_u64 v[226:227], s[14:15], 0, v[140:141]
	ds_read_b128 v[150:153], v7 offset:32768
	ds_read_b128 v[154:157], v7 offset:33792
	ds_read_b128 v[158:161], v7 offset:34816
	ds_read_b128 v[162:165], v7 offset:35840
	ds_read_b128 v[166:169], v7 offset:36864
	ds_read_b128 v[170:173], v7 offset:37888
	ds_read_b128 v[174:177], v7 offset:38912
	ds_read_b128 v[178:181], v7 offset:39936
	ds_read_b128 v[182:185], v194
	ds_read_b128 v[186:189], v194 offset:1024
	ds_read_b128 v[190:193], v194 offset:2048
	ds_read_b128 v[194:197], v194 offset:3072
	ds_read_b128 v[208:211], v207
	ds_read_b128 v[212:215], v207 offset:1024
	ds_read_b128 v[216:219], v207 offset:2048
	ds_read_b128 v[220:223], v207 offset:3072
	global_load_lds_dwordx4 v[226:227], off
	v_lshl_add_u64 v[226:227], s[14:15], 0, v[138:139]
	s_mov_b32 m0, s41
	s_nop 0
	global_load_lds_dwordx4 v[226:227], off
	s_waitcnt vmcnt(8)
	s_waitcnt lgkmcnt(0)
	s_barrier
	s_setprio 1
	s_waitcnt lgkmcnt(0)
	v_mfma_f32_16x16x32_bf16 v[132:135], v[182:185], v[150:153], v[132:135]
	v_mfma_f32_16x16x32_bf16 v[132:135], v[186:189], v[154:157], v[132:135]
	v_mfma_f32_16x16x32_bf16 v[128:131], v[190:193], v[150:153], v[128:131]
	v_mfma_f32_16x16x32_bf16 v[128:131], v[194:197], v[154:157], v[128:131]
	v_mfma_f32_16x16x32_bf16 v[124:127], v[182:185], v[158:161], v[124:127]
	v_mfma_f32_16x16x32_bf16 v[124:127], v[186:189], v[162:165], v[124:127]
	v_mfma_f32_16x16x32_bf16 v[120:123], v[190:193], v[158:161], v[120:123]
	v_mfma_f32_16x16x32_bf16 v[120:123], v[194:197], v[162:165], v[120:123]
	v_mfma_f32_16x16x32_bf16 v[116:119], v[182:185], v[166:169], v[116:119]
	v_mfma_f32_16x16x32_bf16 v[116:119], v[186:189], v[170:173], v[116:119]
	v_mfma_f32_16x16x32_bf16 v[108:111], v[190:193], v[166:169], v[108:111]
	v_mfma_f32_16x16x32_bf16 v[108:111], v[194:197], v[170:173], v[108:111]
	v_mfma_f32_16x16x32_bf16 v[100:103], v[182:185], v[174:177], v[100:103]
	v_mfma_f32_16x16x32_bf16 v[100:103], v[186:189], v[178:181], v[100:103]
	v_mfma_f32_16x16x32_bf16 v[92:95], v[190:193], v[174:177], v[92:95]
	v_mfma_f32_16x16x32_bf16 v[92:95], v[194:197], v[178:181], v[92:95]
	s_setprio 0
	s_setprio 1
	v_mfma_f32_16x16x32_bf16 v[112:115], v[208:211], v[150:153], v[112:115]
	v_mfma_f32_16x16x32_bf16 v[112:115], v[212:215], v[154:157], v[112:115]
	v_mfma_f32_16x16x32_bf16 v[104:107], v[216:219], v[150:153], v[104:107]
	v_mfma_f32_16x16x32_bf16 v[104:107], v[220:223], v[154:157], v[104:107]
	v_mfma_f32_16x16x32_bf16 v[96:99], v[208:211], v[158:161], v[96:99]
	v_mfma_f32_16x16x32_bf16 v[96:99], v[212:215], v[162:165], v[96:99]
	v_mfma_f32_16x16x32_bf16 v[88:91], v[216:219], v[158:161], v[88:91]
	v_mfma_f32_16x16x32_bf16 v[88:91], v[220:223], v[162:165], v[88:91]
	v_mfma_f32_16x16x32_bf16 v[84:87], v[208:211], v[166:169], v[84:87]
	v_mfma_f32_16x16x32_bf16 v[84:87], v[212:215], v[170:173], v[84:87]
	v_mfma_f32_16x16x32_bf16 v[80:83], v[216:219], v[166:169], v[80:83]
	v_mfma_f32_16x16x32_bf16 v[80:83], v[220:223], v[170:173], v[80:83]
	v_mfma_f32_16x16x32_bf16 v[76:79], v[208:211], v[174:177], v[76:79]
	v_mfma_f32_16x16x32_bf16 v[76:79], v[212:215], v[178:181], v[76:79]
	v_mfma_f32_16x16x32_bf16 v[72:75], v[216:219], v[174:177], v[72:75]
	v_mfma_f32_16x16x32_bf16 v[72:75], v[220:223], v[178:181], v[72:75]
	s_setprio 0
	s_barrier
	s_add_i32 s14, s58, s35
	v_lshl_add_u64 v[136:137], v[136:137], 0, s[0:1]
	s_mov_b32 m0, s14
	ds_read_b128 v[150:153], v7 offset:49152
	ds_read_b128 v[154:157], v7 offset:50176
	ds_read_b128 v[158:161], v7 offset:51200
	ds_read_b128 v[162:165], v7 offset:52224
	ds_read_b128 v[166:169], v7 offset:53248
	ds_read_b128 v[170:173], v7 offset:54272
	ds_read_b128 v[174:177], v7 offset:55296
	ds_read_b128 v[178:181], v7 offset:56320
	global_load_lds_dwordx4 v[136:137], off
	s_add_i32 m0, s14, 0x2000
	s_add_u32 s12, s12, 0x20080
	v_lshl_add_u64 v[136:137], v[198:199], 0, s[0:1]
	s_addc_u32 s13, s13, 0
	s_add_i32 s14, s59, s35
	global_load_lds_dwordx4 v[136:137], off
	v_lshl_add_u64 v[136:137], s[12:13], 0, v[2:3]
	s_mov_b32 m0, s14
	s_nop 0
	global_load_lds_dwordx4 v[136:137], off
	v_lshl_add_u64 v[136:137], s[12:13], 0, v[4:5]
	s_add_i32 m0, s14, 0x2000
	s_nop 0
	global_load_lds_dwordx4 v[136:137], off
	v_lshl_add_u64 v[136:137], v[204:205], 0, s[0:1]
	s_mov_b32 m0, s49
	s_nop 0
	global_load_lds_dwordx4 v[136:137], off
	v_lshl_add_u64 v[136:137], v[224:225], 0, s[0:1]
	s_mov_b32 m0, s52
	s_nop 0
	global_load_lds_dwordx4 v[136:137], off
	s_waitcnt vmcnt(8)
	s_waitcnt lgkmcnt(0)
	s_barrier
	s_setprio 1
	s_waitcnt lgkmcnt(0)
	v_mfma_f32_16x16x32_bf16 v[68:71], v[182:185], v[150:153], v[68:71]
	v_mfma_f32_16x16x32_bf16 v[68:71], v[186:189], v[154:157], v[68:71]
	v_mfma_f32_16x16x32_bf16 v[64:67], v[190:193], v[150:153], v[64:67]
	v_mfma_f32_16x16x32_bf16 v[64:67], v[194:197], v[154:157], v[64:67]
	v_mfma_f32_16x16x32_bf16 v[60:63], v[182:185], v[158:161], v[60:63]
	v_mfma_f32_16x16x32_bf16 v[60:63], v[186:189], v[162:165], v[60:63]
	v_mfma_f32_16x16x32_bf16 v[56:59], v[190:193], v[158:161], v[56:59]
	v_mfma_f32_16x16x32_bf16 v[56:59], v[194:197], v[162:165], v[56:59]
	v_mfma_f32_16x16x32_bf16 v[52:55], v[182:185], v[166:169], v[52:55]
	v_mfma_f32_16x16x32_bf16 v[52:55], v[186:189], v[170:173], v[52:55]
	v_mfma_f32_16x16x32_bf16 v[44:47], v[190:193], v[166:169], v[44:47]
	v_mfma_f32_16x16x32_bf16 v[44:47], v[194:197], v[170:173], v[44:47]
	v_mfma_f32_16x16x32_bf16 v[36:39], v[182:185], v[174:177], v[36:39]
	v_mfma_f32_16x16x32_bf16 v[36:39], v[186:189], v[178:181], v[36:39]
	v_mfma_f32_16x16x32_bf16 v[28:31], v[190:193], v[174:177], v[28:31]
	v_mfma_f32_16x16x32_bf16 v[28:31], v[194:197], v[178:181], v[28:31]
	s_setprio 0
	s_setprio 1
	v_mfma_f32_16x16x32_bf16 v[48:51], v[208:211], v[150:153], v[48:51]
	v_mfma_f32_16x16x32_bf16 v[48:51], v[212:215], v[154:157], v[48:51]
	v_mfma_f32_16x16x32_bf16 v[40:43], v[216:219], v[150:153], v[40:43]
	v_mfma_f32_16x16x32_bf16 v[40:43], v[220:223], v[154:157], v[40:43]
	v_mfma_f32_16x16x32_bf16 v[32:35], v[208:211], v[158:161], v[32:35]
	v_mfma_f32_16x16x32_bf16 v[32:35], v[212:215], v[162:165], v[32:35]
	v_mfma_f32_16x16x32_bf16 v[24:27], v[216:219], v[158:161], v[24:27]
	v_mfma_f32_16x16x32_bf16 v[24:27], v[220:223], v[162:165], v[24:27]
	v_mfma_f32_16x16x32_bf16 v[20:23], v[208:211], v[166:169], v[20:23]
	v_mfma_f32_16x16x32_bf16 v[20:23], v[212:215], v[170:173], v[20:23]
	v_mfma_f32_16x16x32_bf16 v[16:19], v[216:219], v[166:169], v[16:19]
	v_mfma_f32_16x16x32_bf16 v[16:19], v[220:223], v[170:173], v[16:19]
	v_mfma_f32_16x16x32_bf16 v[12:15], v[208:211], v[174:177], v[12:15]
	v_mfma_f32_16x16x32_bf16 v[12:15], v[212:215], v[178:181], v[12:15]
	v_mfma_f32_16x16x32_bf16 v[8:11], v[216:219], v[174:177], v[8:11]
	v_mfma_f32_16x16x32_bf16 v[8:11], v[220:223], v[178:181], v[8:11]
	s_setprio 0
	s_barrier
	s_add_i32 s57, s57, 2
	s_add_u32 s42, s42, 0x100
	s_addc_u32 s43, s43, 0
	s_add_u32 s26, s26, 0x100
	s_addc_u32 s27, s27, 0
	s_cmp_gt_u32 s57, 5
	s_cbranch_scc0 .LBB0_620
	s_and_b64 vcc, exec, s[6:7]
	s_cbranch_vccz .LBB0_623
	s_barrier

.LBB0_986:
	s_add_u32 s12, s44, 0xfff80080
	s_addc_u32 s13, s45, -1
	s_cmp_eq_u32 s50, 28
	s_cselect_b32 s15, s18, s13
	s_cselect_b32 s14, s19, s12
	s_cselect_b32 s13, s17, s43
	s_cselect_b32 s12, s21, s33
	s_add_i32 s51, 0, 0x10000
	v_add_u32_e32 v2, s51, v7
	s_add_i32 s63, 0, 0x14000
	ds_read_b128 v[150:153], v155
	ds_read_b128 v[156:159], v155 offset:1024
	ds_read_b128 v[160:163], v155 offset:2048
	ds_read_b128 v[164:167], v155 offset:3072
	ds_read_b128 v[168:171], v155 offset:4096
	ds_read_b128 v[172:175], v155 offset:5120
	ds_read_b128 v[176:179], v155 offset:6144
	ds_read_b128 v[180:183], v155 offset:7168
	ds_read_b128 v[184:187], v2
	ds_read_b128 v[188:191], v2 offset:1024
	ds_read_b128 v[192:195], v2 offset:2048
	ds_read_b128 v[196:199], v2 offset:3072
	v_add_u32_e32 v2, s63, v7
	v_lshl_add_u64 v[224:225], s[44:45], 0, v[146:147]
	s_add_i32 m0, s39, 0xc000
	ds_read_b128 v[208:211], v2
	ds_read_b128 v[212:215], v2 offset:1024
	ds_read_b128 v[216:219], v2 offset:2048
	ds_read_b128 v[220:223], v2 offset:3072
	global_load_lds_dwordx4 v[224:225], off
	v_lshl_add_u64 v[224:225], s[44:45], 0, v[148:149]
	s_add_i32 m0, s39, 0xe000
	s_nop 0
	global_load_lds_dwordx4 v[224:225], off
	s_waitcnt vmcnt(8)
	s_waitcnt lgkmcnt(0)
	s_barrier
	s_setprio 1
	s_waitcnt lgkmcnt(0)
	v_mfma_f32_16x16x32_bf16 v[132:135], v[184:187], v[150:153], v[132:135]
	v_mfma_f32_16x16x32_bf16 v[132:135], v[188:191], v[156:159], v[132:135]
	v_mfma_f32_16x16x32_bf16 v[128:131], v[192:195], v[150:153], v[128:131]
	v_mfma_f32_16x16x32_bf16 v[128:131], v[196:199], v[156:159], v[128:131]
	v_mfma_f32_16x16x32_bf16 v[116:119], v[184:187], v[160:163], v[116:119]
	v_mfma_f32_16x16x32_bf16 v[116:119], v[188:191], v[164:167], v[116:119]
	v_mfma_f32_16x16x32_bf16 v[112:115], v[192:195], v[160:163], v[112:115]
	v_mfma_f32_16x16x32_bf16 v[112:115], v[196:199], v[164:167], v[112:115]
	v_mfma_f32_16x16x32_bf16 v[100:103], v[184:187], v[168:171], v[100:103]
	v_mfma_f32_16x16x32_bf16 v[100:103], v[188:191], v[172:175], v[100:103]
	v_mfma_f32_16x16x32_bf16 v[96:99], v[192:195], v[168:171], v[96:99]
	v_mfma_f32_16x16x32_bf16 v[96:99], v[196:199], v[172:175], v[96:99]
	v_mfma_f32_16x16x32_bf16 v[84:87], v[184:187], v[176:179], v[84:87]
	v_mfma_f32_16x16x32_bf16 v[84:87], v[188:191], v[180:183], v[84:87]
	v_mfma_f32_16x16x32_bf16 v[80:83], v[192:195], v[176:179], v[80:83]
	v_mfma_f32_16x16x32_bf16 v[80:83], v[196:199], v[180:183], v[80:83]
	s_setprio 0
	s_setprio 1
	v_mfma_f32_16x16x32_bf16 v[124:127], v[208:211], v[150:153], v[124:127]
	v_mfma_f32_16x16x32_bf16 v[124:127], v[212:215], v[156:159], v[124:127]
	v_mfma_f32_16x16x32_bf16 v[120:123], v[216:219], v[150:153], v[120:123]
	v_mfma_f32_16x16x32_bf16 v[120:123], v[220:223], v[156:159], v[120:123]
	v_mfma_f32_16x16x32_bf16 v[108:111], v[208:211], v[160:163], v[108:111]
	v_mfma_f32_16x16x32_bf16 v[108:111], v[212:215], v[164:167], v[108:111]
	v_mfma_f32_16x16x32_bf16 v[104:107], v[216:219], v[160:163], v[104:107]
	v_mfma_f32_16x16x32_bf16 v[104:107], v[220:223], v[164:167], v[104:107]
	v_mfma_f32_16x16x32_bf16 v[92:95], v[208:211], v[168:171], v[92:95]
	v_mfma_f32_16x16x32_bf16 v[92:95], v[212:215], v[172:175], v[92:95]
	v_mfma_f32_16x16x32_bf16 v[88:91], v[216:219], v[168:171], v[88:91]
	v_mfma_f32_16x16x32_bf16 v[88:91], v[220:223], v[172:175], v[88:91]
	v_mfma_f32_16x16x32_bf16 v[76:79], v[208:211], v[176:179], v[76:79]
	v_mfma_f32_16x16x32_bf16 v[76:79], v[212:215], v[180:183], v[76:79]
	v_mfma_f32_16x16x32_bf16 v[72:75], v[216:219], v[176:179], v[72:75]
	v_mfma_f32_16x16x32_bf16 v[72:75], v[220:223], v[180:183], v[72:75]
	s_setprio 0
	s_barrier
	s_add_i32 s51, s51, s38
	v_lshl_add_u64 v[224:225], s[12:13], 0, v[138:139]
	s_mov_b32 m0, s51
	ds_read_b128 v[150:153], v155 offset:16384
	ds_read_b128 v[156:159], v155 offset:17408
	ds_read_b128 v[160:163], v155 offset:18432
	ds_read_b128 v[164:167], v155 offset:19456
	ds_read_b128 v[168:171], v155 offset:20480
	ds_read_b128 v[172:175], v155 offset:21504
	ds_read_b128 v[176:179], v155 offset:22528
	ds_read_b128 v[180:183], v155 offset:23552
	global_load_lds_dwordx4 v[224:225], off
	s_add_i32 m0, s51, 0x2000
	s_add_u32 s64, s12, 0x80000
	v_lshl_add_u64 v[226:227], s[12:13], 0, v[4:5]
	s_addc_u32 s65, s13, 0
	s_add_i32 s51, s63, s38
	global_load_lds_dwordx4 v[226:227], off
	v_lshl_add_u64 v[228:229], s[64:65], 0, v[138:139]
	s_mov_b32 m0, s51
	v_lshl_add_u64 v[230:231], s[14:15], 0, v[136:137]
	global_load_lds_dwordx4 v[228:229], off
	v_lshl_add_u64 v[228:229], s[64:65], 0, v[4:5]
	s_add_i32 m0, s51, 0x2000
	s_nop 0
	global_load_lds_dwordx4 v[228:229], off
	v_lshl_add_u64 v[228:229], s[14:15], 0, v[140:141]
	s_mov_b32 m0, s39
	s_nop 0
	global_load_lds_dwordx4 v[228:229], off
	s_mov_b32 m0, s40
	s_nop 0
	global_load_lds_dwordx4 v[230:231], off
	s_waitcnt vmcnt(8)
	s_waitcnt lgkmcnt(0)
	s_barrier
	s_setprio 1
	s_waitcnt lgkmcnt(0)
	v_mfma_f32_16x16x32_bf16 v[68:71], v[184:187], v[150:153], v[68:71]
	v_mfma_f32_16x16x32_bf16 v[68:71], v[188:191], v[156:159], v[68:71]
	v_mfma_f32_16x16x32_bf16 v[64:67], v[192:195], v[150:153], v[64:67]
	v_mfma_f32_16x16x32_bf16 v[64:67], v[196:199], v[156:159], v[64:67]
	v_mfma_f32_16x16x32_bf16 v[52:55], v[184:187], v[160:163], v[52:55]
	v_mfma_f32_16x16x32_bf16 v[52:55], v[188:191], v[164:167], v[52:55]
	v_mfma_f32_16x16x32_bf16 v[48:51], v[192:195], v[160:163], v[48:51]
	v_mfma_f32_16x16x32_bf16 v[48:51], v[196:199], v[164:167], v[48:51]
	v_mfma_f32_16x16x32_bf16 v[36:39], v[184:187], v[168:171], v[36:39]
	v_mfma_f32_16x16x32_bf16 v[36:39], v[188:191], v[172:175], v[36:39]
	v_mfma_f32_16x16x32_bf16 v[32:35], v[192:195], v[168:171], v[32:35]
	v_mfma_f32_16x16x32_bf16 v[32:35], v[196:199], v[172:175], v[32:35]
	v_mfma_f32_16x16x32_bf16 v[20:23], v[184:187], v[176:179], v[20:23]
	v_mfma_f32_16x16x32_bf16 v[20:23], v[188:191], v[180:183], v[20:23]
	v_mfma_f32_16x16x32_bf16 v[16:19], v[192:195], v[176:179], v[16:19]
	v_mfma_f32_16x16x32_bf16 v[16:19], v[196:199], v[180:183], v[16:19]
	s_setprio 0
	s_setprio 1
	v_mfma_f32_16x16x32_bf16 v[60:63], v[208:211], v[150:153], v[60:63]
	v_mfma_f32_16x16x32_bf16 v[60:63], v[212:215], v[156:159], v[60:63]
	v_mfma_f32_16x16x32_bf16 v[56:59], v[216:219], v[150:153], v[56:59]
	v_mfma_f32_16x16x32_bf16 v[56:59], v[220:223], v[156:159], v[56:59]
	v_mfma_f32_16x16x32_bf16 v[44:47], v[208:211], v[160:163], v[44:47]
	v_mfma_f32_16x16x32_bf16 v[44:47], v[212:215], v[164:167], v[44:47]
	v_mfma_f32_16x16x32_bf16 v[40:43], v[216:219], v[160:163], v[40:43]
	v_mfma_f32_16x16x32_bf16 v[40:43], v[220:223], v[164:167], v[40:43]
	v_mfma_f32_16x16x32_bf16 v[28:31], v[208:211], v[168:171], v[28:31]
	v_mfma_f32_16x16x32_bf16 v[28:31], v[212:215], v[172:175], v[28:31]
	v_mfma_f32_16x16x32_bf16 v[24:27], v[216:219], v[168:171], v[24:27]
	v_mfma_f32_16x16x32_bf16 v[24:27], v[220:223], v[172:175], v[24:27]
	v_mfma_f32_16x16x32_bf16 v[12:15], v[208:211], v[176:179], v[12:15]
	v_mfma_f32_16x16x32_bf16 v[12:15], v[212:215], v[180:183], v[12:15]
	v_mfma_f32_16x16x32_bf16 v[8:11], v[216:219], v[176:179], v[8:11]
	v_mfma_f32_16x16x32_bf16 v[8:11], v[220:223], v[180:183], v[8:11]
	s_setprio 0
	s_barrier
	s_add_i32 s51, 0, 0x18000
	s_add_i32 s63, 0, 0x1c000
	s_add_u32 s14, s14, 0x80000
	v_add_u32_e32 v2, s51, v7
	s_addc_u32 s15, s15, 0
	s_mov_b32 m0, s41
	ds_read_b128 v[150:153], v155 offset:32768
	ds_read_b128 v[156:159], v155 offset:33792
	ds_read_b128 v[160:163], v155 offset:34816
	ds_read_b128 v[164:167], v155 offset:35840
	ds_read_b128 v[168:171], v155 offset:36864
	ds_read_b128 v[172:175], v155 offset:37888
	ds_read_b128 v[176:179], v155 offset:38912
	ds_read_b128 v[180:183], v155 offset:39936
	ds_read_b128 v[184:187], v2
	ds_read_b128 v[188:191], v2 offset:1024
	ds_read_b128 v[192:195], v2 offset:2048
	ds_read_b128 v[196:199], v2 offset:3072
	v_add_u32_e32 v2, s63, v7
	v_lshl_add_u64 v[232:233], s[14:15], 0, v[140:141]
	ds_read_b128 v[208:211], v2
	ds_read_b128 v[212:215], v2 offset:1024
	ds_read_b128 v[216:219], v2 offset:2048
	ds_read_b128 v[220:223], v2 offset:3072
	global_load_lds_dwordx4 v[232:233], off
	v_lshl_add_u64 v[232:233], s[14:15], 0, v[136:137]
	s_mov_b32 m0, s47
	s_nop 0
	global_load_lds_dwordx4 v[232:233], off
	s_waitcnt vmcnt(8)
	s_waitcnt lgkmcnt(0)
	s_barrier
	s_setprio 1
	s_waitcnt lgkmcnt(0)
	v_mfma_f32_16x16x32_bf16 v[132:135], v[184:187], v[150:153], v[132:135]
	v_mfma_f32_16x16x32_bf16 v[132:135], v[188:191], v[156:159], v[132:135]
	v_mfma_f32_16x16x32_bf16 v[128:131], v[192:195], v[150:153], v[128:131]
	v_mfma_f32_16x16x32_bf16 v[128:131], v[196:199], v[156:159], v[128:131]
	v_mfma_f32_16x16x32_bf16 v[116:119], v[184:187], v[160:163], v[116:119]
	v_mfma_f32_16x16x32_bf16 v[116:119], v[188:191], v[164:167], v[116:119]
	v_mfma_f32_16x16x32_bf16 v[112:115], v[192:195], v[160:163], v[112:115]
	v_mfma_f32_16x16x32_bf16 v[112:115], v[196:199], v[164:167], v[112:115]
	v_mfma_f32_16x16x32_bf16 v[100:103], v[184:187], v[168:171], v[100:103]
	v_mfma_f32_16x16x32_bf16 v[100:103], v[188:191], v[172:175], v[100:103]
	v_mfma_f32_16x16x32_bf16 v[96:99], v[192:195], v[168:171], v[96:99]
	v_mfma_f32_16x16x32_bf16 v[96:99], v[196:199], v[172:175], v[96:99]
	v_mfma_f32_16x16x32_bf16 v[84:87], v[184:187], v[176:179], v[84:87]
	v_mfma_f32_16x16x32_bf16 v[84:87], v[188:191], v[180:183], v[84:87]
	v_mfma_f32_16x16x32_bf16 v[80:83], v[192:195], v[176:179], v[80:83]
	v_mfma_f32_16x16x32_bf16 v[80:83], v[196:199], v[180:183], v[80:83]
	s_setprio 0
	s_setprio 1
	v_mfma_f32_16x16x32_bf16 v[124:127], v[208:211], v[150:153], v[124:127]
	v_mfma_f32_16x16x32_bf16 v[124:127], v[212:215], v[156:159], v[124:127]
	v_mfma_f32_16x16x32_bf16 v[120:123], v[216:219], v[150:153], v[120:123]
	v_mfma_f32_16x16x32_bf16 v[120:123], v[220:223], v[156:159], v[120:123]
	v_mfma_f32_16x16x32_bf16 v[108:111], v[208:211], v[160:163], v[108:111]
	v_mfma_f32_16x16x32_bf16 v[108:111], v[212:215], v[164:167], v[108:111]
	v_mfma_f32_16x16x32_bf16 v[104:107], v[216:219], v[160:163], v[104:107]
	v_mfma_f32_16x16x32_bf16 v[104:107], v[220:223], v[164:167], v[104:107]
	v_mfma_f32_16x16x32_bf16 v[92:95], v[208:211], v[168:171], v[92:95]
	v_mfma_f32_16x16x32_bf16 v[92:95], v[212:215], v[172:175], v[92:95]
	v_mfma_f32_16x16x32_bf16 v[88:91], v[216:219], v[168:171], v[88:91]
	v_mfma_f32_16x16x32_bf16 v[88:91], v[220:223], v[172:175], v[88:91]
	v_mfma_f32_16x16x32_bf16 v[76:79], v[208:211], v[176:179], v[76:79]
	v_mfma_f32_16x16x32_bf16 v[76:79], v[212:215], v[180:183], v[76:79]
	v_mfma_f32_16x16x32_bf16 v[72:75], v[216:219], v[176:179], v[72:75]
	v_mfma_f32_16x16x32_bf16 v[72:75], v[220:223], v[180:183], v[72:75]
	s_setprio 0
	s_barrier
	s_add_i32 s14, s51, s38
	v_lshl_add_u64 v[224:225], v[224:225], 0, s[0:1]
	s_mov_b32 m0, s14
	ds_read_b128 v[150:153], v155 offset:49152
	ds_read_b128 v[156:159], v155 offset:50176
	ds_read_b128 v[160:163], v155 offset:51200
	ds_read_b128 v[164:167], v155 offset:52224
	ds_read_b128 v[168:171], v155 offset:53248
	ds_read_b128 v[172:175], v155 offset:54272
	ds_read_b128 v[176:179], v155 offset:55296
	ds_read_b128 v[180:183], v155 offset:56320
	global_load_lds_dwordx4 v[224:225], off
	s_add_i32 m0, s14, 0x2000
	s_add_u32 s12, s12, 0x80080
	v_lshl_add_u64 v[224:225], v[226:227], 0, s[0:1]
	s_addc_u32 s13, s13, 0
	s_add_i32 s14, s63, s38
	global_load_lds_dwordx4 v[224:225], off
	v_lshl_add_u64 v[224:225], s[12:13], 0, v[138:139]
	s_mov_b32 m0, s14
	s_nop 0
	global_load_lds_dwordx4 v[224:225], off
	v_lshl_add_u64 v[224:225], s[12:13], 0, v[4:5]
	s_add_i32 m0, s14, 0x2000
	s_nop 0
	global_load_lds_dwordx4 v[224:225], off
	v_lshl_add_u64 v[224:225], v[228:229], 0, s[0:1]
	s_mov_b32 m0, s60
	s_nop 0
	global_load_lds_dwordx4 v[224:225], off
	v_lshl_add_u64 v[224:225], v[230:231], 0, s[0:1]
	s_mov_b32 m0, s61
	s_nop 0
	global_load_lds_dwordx4 v[224:225], off
	s_waitcnt vmcnt(8)
	s_waitcnt lgkmcnt(0)
	s_barrier
	s_setprio 1
	s_waitcnt lgkmcnt(0)
	v_mfma_f32_16x16x32_bf16 v[68:71], v[184:187], v[150:153], v[68:71]
	v_mfma_f32_16x16x32_bf16 v[68:71], v[188:191], v[156:159], v[68:71]
	v_mfma_f32_16x16x32_bf16 v[64:67], v[192:195], v[150:153], v[64:67]
	v_mfma_f32_16x16x32_bf16 v[64:67], v[196:199], v[156:159], v[64:67]
	v_mfma_f32_16x16x32_bf16 v[52:55], v[184:187], v[160:163], v[52:55]
	v_mfma_f32_16x16x32_bf16 v[52:55], v[188:191], v[164:167], v[52:55]
	v_mfma_f32_16x16x32_bf16 v[48:51], v[192:195], v[160:163], v[48:51]
	v_mfma_f32_16x16x32_bf16 v[48:51], v[196:199], v[164:167], v[48:51]
	v_mfma_f32_16x16x32_bf16 v[36:39], v[184:187], v[168:171], v[36:39]
	v_mfma_f32_16x16x32_bf16 v[36:39], v[188:191], v[172:175], v[36:39]
	v_mfma_f32_16x16x32_bf16 v[32:35], v[192:195], v[168:171], v[32:35]
	v_mfma_f32_16x16x32_bf16 v[32:35], v[196:199], v[172:175], v[32:35]
	v_mfma_f32_16x16x32_bf16 v[20:23], v[184:187], v[176:179], v[20:23]
	v_mfma_f32_16x16x32_bf16 v[20:23], v[188:191], v[180:183], v[20:23]
	v_mfma_f32_16x16x32_bf16 v[16:19], v[192:195], v[176:179], v[16:19]
	v_mfma_f32_16x16x32_bf16 v[16:19], v[196:199], v[180:183], v[16:19]
	s_setprio 0
	s_setprio 1
	v_mfma_f32_16x16x32_bf16 v[60:63], v[208:211], v[150:153], v[60:63]
	v_mfma_f32_16x16x32_bf16 v[60:63], v[212:215], v[156:159], v[60:63]
	v_mfma_f32_16x16x32_bf16 v[56:59], v[216:219], v[150:153], v[56:59]
	v_mfma_f32_16x16x32_bf16 v[56:59], v[220:223], v[156:159], v[56:59]
	v_mfma_f32_16x16x32_bf16 v[44:47], v[208:211], v[160:163], v[44:47]
	v_mfma_f32_16x16x32_bf16 v[44:47], v[212:215], v[164:167], v[44:47]
	v_mfma_f32_16x16x32_bf16 v[40:43], v[216:219], v[160:163], v[40:43]
	v_mfma_f32_16x16x32_bf16 v[40:43], v[220:223], v[164:167], v[40:43]
	v_mfma_f32_16x16x32_bf16 v[28:31], v[208:211], v[168:171], v[28:31]
	v_mfma_f32_16x16x32_bf16 v[28:31], v[212:215], v[172:175], v[28:31]
	v_mfma_f32_16x16x32_bf16 v[24:27], v[216:219], v[168:171], v[24:27]
	v_mfma_f32_16x16x32_bf16 v[24:27], v[220:223], v[172:175], v[24:27]
	v_mfma_f32_16x16x32_bf16 v[12:15], v[208:211], v[176:179], v[12:15]
	v_mfma_f32_16x16x32_bf16 v[12:15], v[212:215], v[180:183], v[12:15]
	v_mfma_f32_16x16x32_bf16 v[8:11], v[216:219], v[176:179], v[8:11]
	v_mfma_f32_16x16x32_bf16 v[8:11], v[220:223], v[180:183], v[8:11]
	s_setprio 0
	s_barrier
	s_add_i32 s50, s50, 2
	s_add_u32 s44, s44, 0x100
	s_addc_u32 s45, s45, 0
	s_add_u32 s33, s33, 0x100
	s_addc_u32 s43, s43, 0
	s_cmp_gt_u32 s50, 29
	s_cbranch_scc0 .LBB0_986
	s_and_b64 vcc, exec, s[10:11]
	s_cbranch_vccz .LBB0_1031
	s_barrier
	s_cmp_gt_i32 s35, 15
	s_mov_b64 s[12:13], -1
	s_cbranch_scc1 .LBB0_1032

.LBB0_1482:
	s_add_i32 s26, s12, 2
	s_cmp_eq_u32 s57, s12
	s_cselect_b32 s13, s43, s51
	s_cselect_b32 s12, s42, s50
	s_cselect_b32 s65, s45, s15
	s_cselect_b32 s64, s44, s14
	s_add_i32 s27, 0, 0x10000
	s_movk_i32 s66, 0xff80
	v_add_u32_e32 v121, s27, v7
	s_add_i32 s63, 0, 0x14000
	v_lshl_add_u64 v[178:179], s[50:51], 0, v[108:109]
	s_mov_b32 s67, -1
	ds_read_b128 v[110:113], v119
	ds_read_b128 v[114:117], v119 offset:1024
	ds_read_b128 v[122:125], v119 offset:2048
	ds_read_b128 v[126:129], v119 offset:3072
	ds_read_b128 v[130:133], v119 offset:4096
	ds_read_b128 v[134:137], v119 offset:5120
	ds_read_b128 v[138:141], v119 offset:6144
	ds_read_b128 v[142:145], v119 offset:7168
	ds_read_b128 v[146:149], v121
	ds_read_b128 v[150:153], v121 offset:1024
	ds_read_b128 v[154:157], v121 offset:2048
	ds_read_b128 v[158:161], v121 offset:3072
	v_add_u32_e32 v121, s63, v7
	v_lshl_add_u64 v[178:179], v[178:179], 0, s[66:67]
	s_add_i32 m0, s39, 0xc000
	ds_read_b128 v[162:165], v121
	ds_read_b128 v[166:169], v121 offset:1024
	ds_read_b128 v[170:173], v121 offset:2048
	ds_read_b128 v[174:177], v121 offset:3072
	global_load_lds_dwordx4 v[178:179], off
	s_waitcnt vmcnt(7)
	s_waitcnt lgkmcnt(0)
	s_barrier
	s_setprio 1
	s_waitcnt lgkmcnt(0)
	v_mfma_f32_16x16x32_bf16 v[100:103], v[146:149], v[110:113], v[100:103]
	v_mfma_f32_16x16x32_bf16 v[100:103], v[150:153], v[114:117], v[100:103]
	v_mfma_f32_16x16x32_bf16 v[96:99], v[154:157], v[110:113], v[96:99]
	v_mfma_f32_16x16x32_bf16 v[96:99], v[158:161], v[114:117], v[96:99]
	v_mfma_f32_16x16x32_bf16 v[92:95], v[146:149], v[122:125], v[92:95]
	v_mfma_f32_16x16x32_bf16 v[92:95], v[150:153], v[126:129], v[92:95]
	v_mfma_f32_16x16x32_bf16 v[80:83], v[154:157], v[122:125], v[80:83]
	v_mfma_f32_16x16x32_bf16 v[80:83], v[158:161], v[126:129], v[80:83]
	v_mfma_f32_16x16x32_bf16 v[72:75], v[146:149], v[130:133], v[72:75]
	v_mfma_f32_16x16x32_bf16 v[72:75], v[150:153], v[134:137], v[72:75]
	v_mfma_f32_16x16x32_bf16 v[64:67], v[154:157], v[130:133], v[64:67]
	v_mfma_f32_16x16x32_bf16 v[64:67], v[158:161], v[134:137], v[64:67]
	v_mfma_f32_16x16x32_bf16 v[56:59], v[146:149], v[138:141], v[56:59]
	v_mfma_f32_16x16x32_bf16 v[56:59], v[150:153], v[142:145], v[56:59]
	v_mfma_f32_16x16x32_bf16 v[48:51], v[154:157], v[138:141], v[48:51]
	v_mfma_f32_16x16x32_bf16 v[48:51], v[158:161], v[142:145], v[48:51]
	s_setprio 0
	s_setprio 1
	v_mfma_f32_16x16x32_bf16 v[88:91], v[162:165], v[110:113], v[88:91]
	v_mfma_f32_16x16x32_bf16 v[88:91], v[166:169], v[114:117], v[88:91]
	v_mfma_f32_16x16x32_bf16 v[84:87], v[170:173], v[110:113], v[84:87]
	v_mfma_f32_16x16x32_bf16 v[84:87], v[174:177], v[114:117], v[84:87]
	v_mfma_f32_16x16x32_bf16 v[76:79], v[162:165], v[122:125], v[76:79]
	v_mfma_f32_16x16x32_bf16 v[76:79], v[166:169], v[126:129], v[76:79]
	v_mfma_f32_16x16x32_bf16 v[68:71], v[170:173], v[122:125], v[68:71]
	v_mfma_f32_16x16x32_bf16 v[68:71], v[174:177], v[126:129], v[68:71]
	v_mfma_f32_16x16x32_bf16 v[60:63], v[162:165], v[130:133], v[60:63]
	v_mfma_f32_16x16x32_bf16 v[60:63], v[166:169], v[134:137], v[60:63]
	v_mfma_f32_16x16x32_bf16 v[52:55], v[170:173], v[130:133], v[52:55]
	v_mfma_f32_16x16x32_bf16 v[52:55], v[174:177], v[134:137], v[52:55]
	v_mfma_f32_16x16x32_bf16 v[44:47], v[162:165], v[138:141], v[44:47]
	v_mfma_f32_16x16x32_bf16 v[44:47], v[166:169], v[142:145], v[44:47]
	v_mfma_f32_16x16x32_bf16 v[40:43], v[170:173], v[138:141], v[40:43]
	v_mfma_f32_16x16x32_bf16 v[40:43], v[174:177], v[142:145], v[40:43]
	s_setprio 0
	s_barrier
	s_add_i32 s27, s27, s22
	v_lshl_add_u64 v[178:179], s[64:65], 0, v[2:3]
	s_mov_b32 m0, s27
	ds_read_b128 v[110:113], v120 offset:16384
	ds_read_b128 v[114:117], v120 offset:17408
	ds_read_b128 v[122:125], v120 offset:18432
	ds_read_b128 v[126:129], v120 offset:19456
	global_load_lds_dwordx4 v[178:179], off
	s_add_i32 m0, s27, 0x2000
	v_lshl_add_u64 v[180:181], s[64:65], 0, v[4:5]
	s_add_u32 s64, s64, s90
	s_addc_u32 s65, s65, 0
	s_add_i32 s27, s63, s22
	global_load_lds_dwordx4 v[180:181], off
	v_lshl_add_u64 v[182:183], s[64:65], 0, v[2:3]
	s_mov_b32 m0, s27
	v_lshl_add_u64 v[184:185], s[64:65], 0, v[4:5]
	global_load_lds_dwordx4 v[182:183], off
	s_add_i32 m0, s27, 0x2000
	v_lshl_add_u64 v[186:187], s[12:13], 0, v[106:107]
	global_load_lds_dwordx4 v[184:185], off
	s_mov_b32 m0, s39
	v_lshl_add_u64 v[188:189], s[12:13], 0, v[104:105]
	global_load_lds_dwordx4 v[186:187], off
	s_mov_b32 m0, s40
	s_nop 0
	global_load_lds_dwordx4 v[188:189], off
	s_waitcnt vmcnt(7)
	s_waitcnt lgkmcnt(0)
	s_barrier
	s_setprio 1
	s_waitcnt lgkmcnt(0)
	v_mfma_f32_16x16x32_bf16 v[36:39], v[146:149], v[110:113], v[36:39]
	v_mfma_f32_16x16x32_bf16 v[36:39], v[150:153], v[114:117], v[36:39]
	v_mfma_f32_16x16x32_bf16 v[32:35], v[154:157], v[110:113], v[32:35]
	v_mfma_f32_16x16x32_bf16 v[32:35], v[158:161], v[114:117], v[32:35]
	v_mfma_f32_16x16x32_bf16 v[20:23], v[146:149], v[122:125], v[20:23]
	v_mfma_f32_16x16x32_bf16 v[20:23], v[150:153], v[126:129], v[20:23]
	v_mfma_f32_16x16x32_bf16 v[16:19], v[154:157], v[122:125], v[16:19]
	v_mfma_f32_16x16x32_bf16 v[16:19], v[158:161], v[126:129], v[16:19]
	s_setprio 0
	s_setprio 1
	v_mfma_f32_16x16x32_bf16 v[28:31], v[162:165], v[110:113], v[28:31]
	v_mfma_f32_16x16x32_bf16 v[28:31], v[166:169], v[114:117], v[28:31]
	v_mfma_f32_16x16x32_bf16 v[24:27], v[170:173], v[110:113], v[24:27]
	v_mfma_f32_16x16x32_bf16 v[24:27], v[174:177], v[114:117], v[24:27]
	v_mfma_f32_16x16x32_bf16 v[12:15], v[162:165], v[122:125], v[12:15]
	v_mfma_f32_16x16x32_bf16 v[12:15], v[166:169], v[126:129], v[12:15]
	v_mfma_f32_16x16x32_bf16 v[8:11], v[170:173], v[122:125], v[8:11]
	v_mfma_f32_16x16x32_bf16 v[8:11], v[174:177], v[126:129], v[8:11]
	s_setprio 0
	s_barrier
	s_add_i32 s27, 0, 0x18000
	s_add_i32 s63, 0, 0x1c000
	s_add_u32 s12, s12, s90
	v_add_u32_e32 v121, s27, v7
	s_addc_u32 s13, s13, 0
	ds_read_b128 v[110:113], v119 offset:32768
	ds_read_b128 v[114:117], v119 offset:33792
	ds_read_b128 v[122:125], v119 offset:34816
	ds_read_b128 v[126:129], v119 offset:35840
	ds_read_b128 v[130:133], v119 offset:36864
	ds_read_b128 v[134:137], v119 offset:37888
	ds_read_b128 v[138:141], v119 offset:38912
	ds_read_b128 v[142:145], v119 offset:39936
	ds_read_b128 v[146:149], v121
	ds_read_b128 v[150:153], v121 offset:1024
	ds_read_b128 v[154:157], v121 offset:2048
	ds_read_b128 v[158:161], v121 offset:3072
	v_add_u32_e32 v121, s63, v7
	v_lshl_add_u64 v[190:191], s[12:13], 0, v[106:107]
	s_mov_b32 m0, s41
	ds_read_b128 v[162:165], v121
	ds_read_b128 v[166:169], v121 offset:1024
	ds_read_b128 v[170:173], v121 offset:2048
	ds_read_b128 v[174:177], v121 offset:3072
	global_load_lds_dwordx4 v[190:191], off
	s_waitcnt vmcnt(7)
	s_waitcnt lgkmcnt(0)
	s_barrier
	s_setprio 1
	s_waitcnt lgkmcnt(0)
	v_mfma_f32_16x16x32_bf16 v[100:103], v[146:149], v[110:113], v[100:103]
	v_mfma_f32_16x16x32_bf16 v[100:103], v[150:153], v[114:117], v[100:103]
	v_mfma_f32_16x16x32_bf16 v[96:99], v[154:157], v[110:113], v[96:99]
	v_mfma_f32_16x16x32_bf16 v[96:99], v[158:161], v[114:117], v[96:99]
	v_mfma_f32_16x16x32_bf16 v[92:95], v[146:149], v[122:125], v[92:95]
	v_mfma_f32_16x16x32_bf16 v[92:95], v[150:153], v[126:129], v[92:95]
	v_mfma_f32_16x16x32_bf16 v[80:83], v[154:157], v[122:125], v[80:83]
	v_mfma_f32_16x16x32_bf16 v[80:83], v[158:161], v[126:129], v[80:83]
	v_mfma_f32_16x16x32_bf16 v[72:75], v[146:149], v[130:133], v[72:75]
	v_mfma_f32_16x16x32_bf16 v[72:75], v[150:153], v[134:137], v[72:75]
	v_mfma_f32_16x16x32_bf16 v[64:67], v[154:157], v[130:133], v[64:67]
	v_mfma_f32_16x16x32_bf16 v[64:67], v[158:161], v[134:137], v[64:67]
	v_mfma_f32_16x16x32_bf16 v[56:59], v[146:149], v[138:141], v[56:59]
	v_mfma_f32_16x16x32_bf16 v[56:59], v[150:153], v[142:145], v[56:59]
	v_mfma_f32_16x16x32_bf16 v[48:51], v[154:157], v[138:141], v[48:51]
	v_mfma_f32_16x16x32_bf16 v[48:51], v[158:161], v[142:145], v[48:51]
	s_setprio 0
	s_setprio 1
	v_mfma_f32_16x16x32_bf16 v[88:91], v[162:165], v[110:113], v[88:91]
	v_mfma_f32_16x16x32_bf16 v[88:91], v[166:169], v[114:117], v[88:91]
	v_mfma_f32_16x16x32_bf16 v[84:87], v[170:173], v[110:113], v[84:87]
	v_mfma_f32_16x16x32_bf16 v[84:87], v[174:177], v[114:117], v[84:87]
	v_mfma_f32_16x16x32_bf16 v[76:79], v[162:165], v[122:125], v[76:79]
	v_mfma_f32_16x16x32_bf16 v[76:79], v[166:169], v[126:129], v[76:79]
	v_mfma_f32_16x16x32_bf16 v[68:71], v[170:173], v[122:125], v[68:71]
	v_mfma_f32_16x16x32_bf16 v[68:71], v[174:177], v[126:129], v[68:71]
	v_mfma_f32_16x16x32_bf16 v[60:63], v[162:165], v[130:133], v[60:63]
	v_mfma_f32_16x16x32_bf16 v[60:63], v[166:169], v[134:137], v[60:63]
	v_mfma_f32_16x16x32_bf16 v[52:55], v[170:173], v[130:133], v[52:55]
	v_mfma_f32_16x16x32_bf16 v[52:55], v[174:177], v[134:137], v[52:55]
	v_mfma_f32_16x16x32_bf16 v[44:47], v[162:165], v[138:141], v[44:47]
	v_mfma_f32_16x16x32_bf16 v[44:47], v[166:169], v[142:145], v[44:47]
	v_mfma_f32_16x16x32_bf16 v[40:43], v[170:173], v[138:141], v[40:43]
	v_mfma_f32_16x16x32_bf16 v[40:43], v[174:177], v[142:145], v[40:43]
	s_setprio 0
	s_barrier
	s_add_i32 s12, s27, s22
	v_lshl_add_u64 v[130:131], v[178:179], 0, s[0:1]
	s_mov_b32 m0, s12
	ds_read_b128 v[110:113], v120 offset:49152
	ds_read_b128 v[114:117], v120 offset:50176
	ds_read_b128 v[122:125], v120 offset:51200
	ds_read_b128 v[126:129], v120 offset:52224
	global_load_lds_dwordx4 v[130:131], off
	v_lshl_add_u64 v[130:131], v[180:181], 0, s[0:1]
	s_add_i32 m0, s12, 0x2000
	s_add_i32 s12, s63, s22
	global_load_lds_dwordx4 v[130:131], off
	v_lshl_add_u64 v[130:131], v[182:183], 0, s[0:1]
	s_mov_b32 m0, s12
	s_nop 0
	global_load_lds_dwordx4 v[130:131], off
	v_lshl_add_u64 v[130:131], v[184:185], 0, s[0:1]
	s_add_i32 m0, s12, 0x2000
	s_nop 0
	global_load_lds_dwordx4 v[130:131], off
	v_lshl_add_u64 v[130:131], v[186:187], 0, s[0:1]
	s_mov_b32 m0, s53
	s_nop 0
	global_load_lds_dwordx4 v[130:131], off
	v_lshl_add_u64 v[130:131], v[188:189], 0, s[0:1]
	s_mov_b32 m0, s54
	s_nop 0
	global_load_lds_dwordx4 v[130:131], off
	s_waitcnt vmcnt(7)
	s_waitcnt lgkmcnt(0)
	s_barrier
	s_setprio 1
	s_waitcnt lgkmcnt(0)
	v_mfma_f32_16x16x32_bf16 v[36:39], v[146:149], v[110:113], v[36:39]
	v_mfma_f32_16x16x32_bf16 v[36:39], v[150:153], v[114:117], v[36:39]
	v_mfma_f32_16x16x32_bf16 v[32:35], v[154:157], v[110:113], v[32:35]
	v_mfma_f32_16x16x32_bf16 v[32:35], v[158:161], v[114:117], v[32:35]
	v_mfma_f32_16x16x32_bf16 v[20:23], v[146:149], v[122:125], v[20:23]
	v_mfma_f32_16x16x32_bf16 v[20:23], v[150:153], v[126:129], v[20:23]
	v_mfma_f32_16x16x32_bf16 v[16:19], v[154:157], v[122:125], v[16:19]
	v_mfma_f32_16x16x32_bf16 v[16:19], v[158:161], v[126:129], v[16:19]
	s_setprio 0
	s_setprio 1
	v_mfma_f32_16x16x32_bf16 v[28:31], v[162:165], v[110:113], v[28:31]
	v_mfma_f32_16x16x32_bf16 v[28:31], v[166:169], v[114:117], v[28:31]
	v_mfma_f32_16x16x32_bf16 v[24:27], v[170:173], v[110:113], v[24:27]
	v_mfma_f32_16x16x32_bf16 v[24:27], v[174:177], v[114:117], v[24:27]
	v_mfma_f32_16x16x32_bf16 v[12:15], v[162:165], v[122:125], v[12:15]
	v_mfma_f32_16x16x32_bf16 v[12:15], v[166:169], v[126:129], v[12:15]
	v_mfma_f32_16x16x32_bf16 v[8:11], v[170:173], v[122:125], v[8:11]
	v_mfma_f32_16x16x32_bf16 v[8:11], v[174:177], v[126:129], v[8:11]
	s_setprio 0
	s_barrier
	s_add_u32 s50, s50, 0x100
	s_addc_u32 s51, s51, 0
	s_add_u32 s14, s14, 0x100
	s_addc_u32 s15, s15, 0
	s_cmp_ge_u32 s26, s55
	s_mov_b32 s12, s26
	s_cbranch_scc0 .LBB0_1482
	s_and_b64 vcc, exec, s[36:37]
	s_cbranch_vccz .LBB0_1485
	s_barrier
